# full pipeline rebuild: inproj0 B-fragment ring 7 / lookahead 6, accumulators started with C=0, outproj pipelined loops
# baseline (speedup 1.0000x reference)
.LBB0_171:
	s_lshr_b32 s88, s75, 3
	s_lshl_b32 s88, s88, 4
	s_and_b32 s90, s75, 7
	s_or_b32 s88, s88, s90
	s_lshl_b32 s90, s89, 3
	s_add_i32 s88, s88, s90
	s_ashr_i32 s1, s88, 31
	s_lshr_b32 s1, s1, 23
	s_add_i32 s1, s88, s1
	s_ashr_i32 s1, s1, 9
	s_and_b32 s0, s88, 7
	s_lshl_b32 s1, s1, 3
	s_or_b32 s34, s1, s0
	s_mul_hi_i32 s0, s34, 0x92492493
	s_add_i32 s0, s0, s34
	s_lshr_b32 s1, s0, 31
	s_ashr_i32 s70, s0, 2
	s_add_i32 s70, s70, s1
	s_lshl_b32 s0, s70, 3
	s_bfe_u32 s1, s88, 0x30003
	s_or_b32 s66, s0, s1
	s_mul_i32 s0, s70, 7
	s_sub_i32 s77, s34, s0
	s_lshl_b32 s0, s77, 3
	s_bfe_u32 s76, s88, 0x30006
	s_or_b32 s0, s0, s76
	s_ashr_i32 s67, s66, 31
	s_ashr_i32 s1, s0, 31
	s_lshl_b64 s[4:5], s[0:1], 18
	s_lshl_b64 s[6:7], s[66:67], 18
	s_cmp_lg_u32 s89, 0
	s_cbranch_scc1 .Lmy_ip0_pass2
	s_barrier
	s_setprio 2
	s_lshl_b64 s[64:65], s[66:67], 17
	s_add_u32 s84, s50, 0x3a00000
	s_addc_u32 s85, s51, 0
	s_add_u32 s84, s84, s6
	s_addc_u32 s85, s85, s7
	s_add_u32 s92, s84, 0x40000
	s_addc_u32 s93, s85, 0
	s_add_u32 s86, s50, 0x1a00000
	s_addc_u32 s87, s51, 0
	s_add_u32 s86, s86, s4
	s_addc_u32 s87, s87, s5
	v_readfirstlane_b32 s1, v129
	v_and_b32_e32 v200, 15, v131
	v_bfe_u32 v201, v131, 4, 2
	v_and_b32_e32 v202, 63, v131
	v_lshlrev_b32_e32 v202, 4, v202
	v_lshrrev_b32_e32 v203, 6, v131
	v_lshl_add_u32 v142, v203, 16, v202
	v_add_u32_e32 v150, 0x8000, v142
	v_bfe_u32 v202, v131, 1, 3
	v_xor_b32_e32 v202, v201, v202
	v_lshlrev_b32_e32 v202, 4, v202
	v_lshl_or_b32 v212, v200, 7, v202
	v_xor_b32_e32 v213, 64, v212
	v_bfe_u32 v200, v131, 4, 3
	v_and_b32_e32 v201, 7, v131
	v_xor_b32_e32 v200, v200, v201
	v_lshlrev_b32_e32 v200, 4, v200
	v_lshrrev_b32_e32 v201, 3, v131
	v_lshl_or_b32 v151, v201, 11, v200
	v_add_u32_e32 v156, 65536, v151
	v_add_u32_e32 v158, 131072, v151
	v_add_u32_e32 v159, 196608, v151
	s_add_u32 m0, s1, 0
	s_nop 0
	global_load_lds_dwordx4 v151, s[86:87]
	s_add_u32 m0, s1, 4096
	s_nop 0
	global_load_lds_dwordx4 v156, s[86:87]
	s_add_u32 m0, s1, 8192
	s_nop 0
	global_load_lds_dwordx4 v158, s[86:87]
	s_add_u32 m0, s1, 12288
	s_nop 0
	global_load_lds_dwordx4 v159, s[86:87]
	s_add_u32 s86, s86, 128
	s_addc_u32 s87, s87, 0
	global_load_dwordx4 v[64:67], v142, s[84:85] offset:0
	global_load_dwordx4 v[68:71], v150, s[84:85] offset:0
	global_load_dwordx4 v[72:75], v142, s[92:93] offset:0
	global_load_dwordx4 v[76:79], v150, s[92:93] offset:0
	global_load_dwordx4 v[80:83], v142, s[84:85] offset:1024
	global_load_dwordx4 v[84:87], v150, s[84:85] offset:1024
	global_load_dwordx4 v[88:91], v142, s[92:93] offset:1024
	global_load_dwordx4 v[92:95], v150, s[92:93] offset:1024
	s_add_u32 s84, s84, 0x800
	s_addc_u32 s85, s85, 0
	s_add_u32 s92, s92, 0x800
	s_addc_u32 s93, s93, 0
	s_add_u32 m0, s1, 16384
	s_nop 0
	global_load_lds_dwordx4 v151, s[86:87]
	s_add_u32 m0, s1, 20480
	s_nop 0
	global_load_lds_dwordx4 v156, s[86:87]
	s_add_u32 m0, s1, 24576
	s_nop 0
	global_load_lds_dwordx4 v158, s[86:87]
	s_add_u32 m0, s1, 28672
	s_nop 0
	global_load_lds_dwordx4 v159, s[86:87]
	s_add_u32 s86, s86, 128
	s_addc_u32 s87, s87, 0
	s_add_u32 m0, s1, 32768
	s_nop 0
	global_load_lds_dwordx4 v151, s[86:87]
	s_add_u32 m0, s1, 36864
	s_nop 0
	global_load_lds_dwordx4 v156, s[86:87]
	s_add_u32 m0, s1, 40960
	s_nop 0
	global_load_lds_dwordx4 v158, s[86:87]
	s_add_u32 m0, s1, 45056
	s_nop 0
	global_load_lds_dwordx4 v159, s[86:87]
	s_add_u32 s86, s86, 128
	s_addc_u32 s87, s87, 0
	s_waitcnt vmcnt(12)
	s_barrier
	ds_read_b128 v[160:163], v212 offset:0
	ds_read_b128 v[176:179], v212 offset:2048
	ds_read_b128 v[180:183], v212 offset:4096
	ds_read_b128 v[188:191], v212 offset:6144
	ds_read_b128 v[192:195], v212 offset:8192
	ds_read_b128 v[196:199], v212 offset:10240
	ds_read_b128 v[200:203], v212 offset:12288
	global_load_dwordx4 v[96:99], v142, s[84:85] offset:0
	s_waitcnt lgkmcnt(6)
	v_mfma_f32_16x16x32_bf16 v[0:3], v[64:67], v[160:163], 0
	v_mfma_f32_16x16x32_bf16 v[32:35], v[68:71], v[160:163], 0
	v_mfma_f32_16x16x32_bf16 v[144:147], v[72:75], v[160:163], 0
	v_mfma_f32_16x16x32_bf16 v[252:255], v[76:79], v[160:163], 0
	ds_read_b128 v[160:163], v212 offset:14336
	global_load_dwordx4 v[164:167], v150, s[84:85] offset:0
	s_waitcnt lgkmcnt(6)
	v_mfma_f32_16x16x32_bf16 v[4:7], v[64:67], v[176:179], 0
	v_mfma_f32_16x16x32_bf16 v[36:39], v[68:71], v[176:179], 0
	v_mfma_f32_16x16x32_bf16 v[184:187], v[72:75], v[176:179], 0
	v_mfma_f32_16x16x32_bf16 v[100:103], v[76:79], v[176:179], 0
	ds_read_b128 v[176:179], v213 offset:0
	global_load_dwordx4 v[168:171], v142, s[92:93] offset:0
	s_waitcnt lgkmcnt(6)
	v_mfma_f32_16x16x32_bf16 v[8:11], v[64:67], v[180:183], 0
	v_mfma_f32_16x16x32_bf16 v[40:43], v[68:71], v[180:183], 0
	v_mfma_f32_16x16x32_bf16 v[204:207], v[72:75], v[180:183], 0
	v_mfma_f32_16x16x32_bf16 v[104:107], v[76:79], v[180:183], 0
	ds_read_b128 v[180:183], v213 offset:2048
	global_load_dwordx4 v[172:175], v150, s[92:93] offset:0
	s_waitcnt lgkmcnt(6)
	v_mfma_f32_16x16x32_bf16 v[12:15], v[64:67], v[188:191], 0
	v_mfma_f32_16x16x32_bf16 v[44:47], v[68:71], v[188:191], 0
	v_mfma_f32_16x16x32_bf16 v[208:211], v[72:75], v[188:191], 0
	v_mfma_f32_16x16x32_bf16 v[108:111], v[76:79], v[188:191], 0
	ds_read_b128 v[188:191], v213 offset:4096
	s_waitcnt lgkmcnt(6)
	v_mfma_f32_16x16x32_bf16 v[16:19], v[64:67], v[192:195], 0
	v_mfma_f32_16x16x32_bf16 v[48:51], v[68:71], v[192:195], 0
	v_mfma_f32_16x16x32_bf16 v[232:235], v[72:75], v[192:195], 0
	v_mfma_f32_16x16x32_bf16 v[112:115], v[76:79], v[192:195], 0
	ds_read_b128 v[192:195], v213 offset:6144
	s_waitcnt lgkmcnt(6)
	v_mfma_f32_16x16x32_bf16 v[20:23], v[64:67], v[196:199], 0
	v_mfma_f32_16x16x32_bf16 v[52:55], v[68:71], v[196:199], 0
	v_mfma_f32_16x16x32_bf16 v[236:239], v[72:75], v[196:199], 0
	v_mfma_f32_16x16x32_bf16 v[116:119], v[76:79], v[196:199], 0
	ds_read_b128 v[196:199], v213 offset:8192
	s_waitcnt lgkmcnt(6)
	v_mfma_f32_16x16x32_bf16 v[24:27], v[64:67], v[200:203], 0
	v_mfma_f32_16x16x32_bf16 v[56:59], v[68:71], v[200:203], 0
	v_mfma_f32_16x16x32_bf16 v[240:243], v[72:75], v[200:203], 0
	v_mfma_f32_16x16x32_bf16 v[120:123], v[76:79], v[200:203], 0
	ds_read_b128 v[200:203], v213 offset:10240
	s_waitcnt lgkmcnt(6)
	v_mfma_f32_16x16x32_bf16 v[28:31], v[64:67], v[160:163], 0
	v_mfma_f32_16x16x32_bf16 v[60:63], v[68:71], v[160:163], 0
	v_mfma_f32_16x16x32_bf16 v[248:251], v[72:75], v[160:163], 0
	v_mfma_f32_16x16x32_bf16 v[124:127], v[76:79], v[160:163], 0
	s_waitcnt vmcnt(8)
	s_barrier
	s_waitcnt vmcnt(12)
	ds_read_b128 v[160:163], v213 offset:12288
	global_load_dwordx4 v[64:67], v142, s[84:85] offset:1024
	s_waitcnt lgkmcnt(6)
	v_mfma_f32_16x16x32_bf16 v[0:3], v[80:83], v[176:179], v[0:3]
	v_mfma_f32_16x16x32_bf16 v[32:35], v[84:87], v[176:179], v[32:35]
	v_mfma_f32_16x16x32_bf16 v[144:147], v[88:91], v[176:179], v[144:147]
	v_mfma_f32_16x16x32_bf16 v[252:255], v[92:95], v[176:179], v[252:255]
	ds_read_b128 v[176:179], v213 offset:14336
	global_load_dwordx4 v[68:71], v150, s[84:85] offset:1024
	s_waitcnt lgkmcnt(6)
	v_mfma_f32_16x16x32_bf16 v[4:7], v[80:83], v[180:183], v[4:7]
	v_mfma_f32_16x16x32_bf16 v[36:39], v[84:87], v[180:183], v[36:39]
	v_mfma_f32_16x16x32_bf16 v[184:187], v[88:91], v[180:183], v[184:187]
	v_mfma_f32_16x16x32_bf16 v[100:103], v[92:95], v[180:183], v[100:103]
	ds_read_b128 v[180:183], v212 offset:16384
	global_load_dwordx4 v[72:75], v142, s[92:93] offset:1024
	s_waitcnt lgkmcnt(6)
	v_mfma_f32_16x16x32_bf16 v[8:11], v[80:83], v[188:191], v[8:11]
	v_mfma_f32_16x16x32_bf16 v[40:43], v[84:87], v[188:191], v[40:43]
	v_mfma_f32_16x16x32_bf16 v[204:207], v[88:91], v[188:191], v[204:207]
	v_mfma_f32_16x16x32_bf16 v[104:107], v[92:95], v[188:191], v[104:107]
	ds_read_b128 v[188:191], v212 offset:18432
	global_load_dwordx4 v[76:79], v150, s[92:93] offset:1024
	s_add_u32 s84, s84, 0x800
	s_addc_u32 s85, s85, 0
	s_add_u32 s92, s92, 0x800
	s_addc_u32 s93, s93, 0
	s_waitcnt lgkmcnt(6)
	v_mfma_f32_16x16x32_bf16 v[12:15], v[80:83], v[192:195], v[12:15]
	v_mfma_f32_16x16x32_bf16 v[44:47], v[84:87], v[192:195], v[44:47]
	v_mfma_f32_16x16x32_bf16 v[208:211], v[88:91], v[192:195], v[208:211]
	v_mfma_f32_16x16x32_bf16 v[108:111], v[92:95], v[192:195], v[108:111]
	ds_read_b128 v[192:195], v212 offset:20480
	s_add_u32 m0, s1, 49152
	s_nop 0
	global_load_lds_dwordx4 v151, s[86:87]
	s_waitcnt lgkmcnt(6)
	v_mfma_f32_16x16x32_bf16 v[16:19], v[80:83], v[196:199], v[16:19]
	v_mfma_f32_16x16x32_bf16 v[48:51], v[84:87], v[196:199], v[48:51]
	v_mfma_f32_16x16x32_bf16 v[232:235], v[88:91], v[196:199], v[232:235]
	v_mfma_f32_16x16x32_bf16 v[112:115], v[92:95], v[196:199], v[112:115]
	ds_read_b128 v[196:199], v212 offset:22528
	s_add_u32 m0, s1, 53248
	s_nop 0
	global_load_lds_dwordx4 v156, s[86:87]
	s_waitcnt lgkmcnt(6)
	v_mfma_f32_16x16x32_bf16 v[20:23], v[80:83], v[200:203], v[20:23]
	v_mfma_f32_16x16x32_bf16 v[52:55], v[84:87], v[200:203], v[52:55]
	v_mfma_f32_16x16x32_bf16 v[236:239], v[88:91], v[200:203], v[236:239]
	v_mfma_f32_16x16x32_bf16 v[116:119], v[92:95], v[200:203], v[116:119]
	ds_read_b128 v[200:203], v212 offset:24576
	s_add_u32 m0, s1, 57344
	s_nop 0
	global_load_lds_dwordx4 v158, s[86:87]
	s_waitcnt lgkmcnt(6)
	v_mfma_f32_16x16x32_bf16 v[24:27], v[80:83], v[160:163], v[24:27]
	v_mfma_f32_16x16x32_bf16 v[56:59], v[84:87], v[160:163], v[56:59]
	v_mfma_f32_16x16x32_bf16 v[240:243], v[88:91], v[160:163], v[240:243]
	v_mfma_f32_16x16x32_bf16 v[120:123], v[92:95], v[160:163], v[120:123]
	ds_read_b128 v[160:163], v212 offset:26624
	s_add_u32 m0, s1, 61440
	s_nop 0
	global_load_lds_dwordx4 v159, s[86:87]
	s_add_u32 s86, s86, 128
	s_addc_u32 s87, s87, 0
	s_waitcnt lgkmcnt(6)
	v_mfma_f32_16x16x32_bf16 v[28:31], v[80:83], v[176:179], v[28:31]
	v_mfma_f32_16x16x32_bf16 v[60:63], v[84:87], v[176:179], v[60:63]
	v_mfma_f32_16x16x32_bf16 v[248:251], v[88:91], v[176:179], v[248:251]
	v_mfma_f32_16x16x32_bf16 v[124:127], v[92:95], v[176:179], v[124:127]
	s_waitcnt vmcnt(8)
	ds_read_b128 v[176:179], v212 offset:28672
	global_load_dwordx4 v[80:83], v142, s[84:85] offset:0
	s_waitcnt lgkmcnt(6)
	v_mfma_f32_16x16x32_bf16 v[0:3], v[96:99], v[180:183], v[0:3]
	v_mfma_f32_16x16x32_bf16 v[32:35], v[164:167], v[180:183], v[32:35]
	v_mfma_f32_16x16x32_bf16 v[144:147], v[168:171], v[180:183], v[144:147]
	v_mfma_f32_16x16x32_bf16 v[252:255], v[172:175], v[180:183], v[252:255]
	ds_read_b128 v[180:183], v212 offset:30720
	global_load_dwordx4 v[84:87], v150, s[84:85] offset:0
	s_waitcnt lgkmcnt(6)
	v_mfma_f32_16x16x32_bf16 v[4:7], v[96:99], v[188:191], v[4:7]
	v_mfma_f32_16x16x32_bf16 v[36:39], v[164:167], v[188:191], v[36:39]
	v_mfma_f32_16x16x32_bf16 v[184:187], v[168:171], v[188:191], v[184:187]
	v_mfma_f32_16x16x32_bf16 v[100:103], v[172:175], v[188:191], v[100:103]
	ds_read_b128 v[188:191], v213 offset:16384
	global_load_dwordx4 v[88:91], v142, s[92:93] offset:0
	s_waitcnt lgkmcnt(6)
	v_mfma_f32_16x16x32_bf16 v[8:11], v[96:99], v[192:195], v[8:11]
	v_mfma_f32_16x16x32_bf16 v[40:43], v[164:167], v[192:195], v[40:43]
	v_mfma_f32_16x16x32_bf16 v[204:207], v[168:171], v[192:195], v[204:207]
	v_mfma_f32_16x16x32_bf16 v[104:107], v[172:175], v[192:195], v[104:107]
	ds_read_b128 v[192:195], v213 offset:18432
	global_load_dwordx4 v[92:95], v150, s[92:93] offset:0
	s_waitcnt lgkmcnt(6)
	v_mfma_f32_16x16x32_bf16 v[12:15], v[96:99], v[196:199], v[12:15]
	v_mfma_f32_16x16x32_bf16 v[44:47], v[164:167], v[196:199], v[44:47]
	v_mfma_f32_16x16x32_bf16 v[208:211], v[168:171], v[196:199], v[208:211]
	v_mfma_f32_16x16x32_bf16 v[108:111], v[172:175], v[196:199], v[108:111]
	ds_read_b128 v[196:199], v213 offset:20480
	s_waitcnt lgkmcnt(6)
	v_mfma_f32_16x16x32_bf16 v[16:19], v[96:99], v[200:203], v[16:19]
	v_mfma_f32_16x16x32_bf16 v[48:51], v[164:167], v[200:203], v[48:51]
	v_mfma_f32_16x16x32_bf16 v[232:235], v[168:171], v[200:203], v[232:235]
	v_mfma_f32_16x16x32_bf16 v[112:115], v[172:175], v[200:203], v[112:115]
	ds_read_b128 v[200:203], v213 offset:22528
	s_waitcnt lgkmcnt(6)
	v_mfma_f32_16x16x32_bf16 v[20:23], v[96:99], v[160:163], v[20:23]
	v_mfma_f32_16x16x32_bf16 v[52:55], v[164:167], v[160:163], v[52:55]
	v_mfma_f32_16x16x32_bf16 v[236:239], v[168:171], v[160:163], v[236:239]
	v_mfma_f32_16x16x32_bf16 v[116:119], v[172:175], v[160:163], v[116:119]
	ds_read_b128 v[160:163], v213 offset:24576
	s_waitcnt lgkmcnt(6)
	v_mfma_f32_16x16x32_bf16 v[24:27], v[96:99], v[176:179], v[24:27]
	v_mfma_f32_16x16x32_bf16 v[56:59], v[164:167], v[176:179], v[56:59]
	v_mfma_f32_16x16x32_bf16 v[240:243], v[168:171], v[176:179], v[240:243]
	v_mfma_f32_16x16x32_bf16 v[120:123], v[172:175], v[176:179], v[120:123]
	ds_read_b128 v[176:179], v213 offset:26624
	s_waitcnt lgkmcnt(6)
	v_mfma_f32_16x16x32_bf16 v[28:31], v[96:99], v[180:183], v[28:31]
	v_mfma_f32_16x16x32_bf16 v[60:63], v[164:167], v[180:183], v[60:63]
	v_mfma_f32_16x16x32_bf16 v[248:251], v[168:171], v[180:183], v[248:251]
	v_mfma_f32_16x16x32_bf16 v[124:127], v[172:175], v[180:183], v[124:127]
	s_waitcnt vmcnt(16)
	s_barrier
	s_waitcnt vmcnt(8)
	ds_read_b128 v[180:183], v213 offset:28672
	global_load_dwordx4 v[96:99], v142, s[84:85] offset:1024
	s_waitcnt lgkmcnt(6)
	v_mfma_f32_16x16x32_bf16 v[0:3], v[64:67], v[188:191], v[0:3]
	v_mfma_f32_16x16x32_bf16 v[32:35], v[68:71], v[188:191], v[32:35]
	v_mfma_f32_16x16x32_bf16 v[144:147], v[72:75], v[188:191], v[144:147]
	v_mfma_f32_16x16x32_bf16 v[252:255], v[76:79], v[188:191], v[252:255]
	ds_read_b128 v[188:191], v213 offset:30720
	global_load_dwordx4 v[164:167], v150, s[84:85] offset:1024
	s_waitcnt lgkmcnt(6)
	v_mfma_f32_16x16x32_bf16 v[4:7], v[64:67], v[192:195], v[4:7]
	v_mfma_f32_16x16x32_bf16 v[36:39], v[68:71], v[192:195], v[36:39]
	v_mfma_f32_16x16x32_bf16 v[184:187], v[72:75], v[192:195], v[184:187]
	v_mfma_f32_16x16x32_bf16 v[100:103], v[76:79], v[192:195], v[100:103]
	ds_read_b128 v[192:195], v212 offset:32768
	global_load_dwordx4 v[168:171], v142, s[92:93] offset:1024
	s_waitcnt lgkmcnt(6)
	v_mfma_f32_16x16x32_bf16 v[8:11], v[64:67], v[196:199], v[8:11]
	v_mfma_f32_16x16x32_bf16 v[40:43], v[68:71], v[196:199], v[40:43]
	v_mfma_f32_16x16x32_bf16 v[204:207], v[72:75], v[196:199], v[204:207]
	v_mfma_f32_16x16x32_bf16 v[104:107], v[76:79], v[196:199], v[104:107]
	ds_read_b128 v[196:199], v212 offset:34816
	global_load_dwordx4 v[172:175], v150, s[92:93] offset:1024
	s_add_u32 s84, s84, 0x800
	s_addc_u32 s85, s85, 0
	s_add_u32 s92, s92, 0x800
	s_addc_u32 s93, s93, 0
	s_waitcnt lgkmcnt(6)
	v_mfma_f32_16x16x32_bf16 v[12:15], v[64:67], v[200:203], v[12:15]
	v_mfma_f32_16x16x32_bf16 v[44:47], v[68:71], v[200:203], v[44:47]
	v_mfma_f32_16x16x32_bf16 v[208:211], v[72:75], v[200:203], v[208:211]
	v_mfma_f32_16x16x32_bf16 v[108:111], v[76:79], v[200:203], v[108:111]
	ds_read_b128 v[200:203], v212 offset:36864
	s_add_u32 m0, s1, 0
	s_nop 0
	global_load_lds_dwordx4 v151, s[86:87]
	s_waitcnt lgkmcnt(6)
	v_mfma_f32_16x16x32_bf16 v[16:19], v[64:67], v[160:163], v[16:19]
	v_mfma_f32_16x16x32_bf16 v[48:51], v[68:71], v[160:163], v[48:51]
	v_mfma_f32_16x16x32_bf16 v[232:235], v[72:75], v[160:163], v[232:235]
	v_mfma_f32_16x16x32_bf16 v[112:115], v[76:79], v[160:163], v[112:115]
	ds_read_b128 v[160:163], v212 offset:38912
	s_add_u32 m0, s1, 4096
	s_nop 0
	global_load_lds_dwordx4 v156, s[86:87]
	s_waitcnt lgkmcnt(6)
	v_mfma_f32_16x16x32_bf16 v[20:23], v[64:67], v[176:179], v[20:23]
	v_mfma_f32_16x16x32_bf16 v[52:55], v[68:71], v[176:179], v[52:55]
	v_mfma_f32_16x16x32_bf16 v[236:239], v[72:75], v[176:179], v[236:239]
	v_mfma_f32_16x16x32_bf16 v[116:119], v[76:79], v[176:179], v[116:119]
	ds_read_b128 v[176:179], v212 offset:40960
	s_add_u32 m0, s1, 8192
	s_nop 0
	global_load_lds_dwordx4 v158, s[86:87]
	s_waitcnt lgkmcnt(6)
	v_mfma_f32_16x16x32_bf16 v[24:27], v[64:67], v[180:183], v[24:27]
	v_mfma_f32_16x16x32_bf16 v[56:59], v[68:71], v[180:183], v[56:59]
	v_mfma_f32_16x16x32_bf16 v[240:243], v[72:75], v[180:183], v[240:243]
	v_mfma_f32_16x16x32_bf16 v[120:123], v[76:79], v[180:183], v[120:123]
	ds_read_b128 v[180:183], v212 offset:43008
	s_add_u32 m0, s1, 12288
	s_nop 0
	global_load_lds_dwordx4 v159, s[86:87]
	s_add_u32 s86, s86, 128
	s_addc_u32 s87, s87, 0
	s_waitcnt lgkmcnt(6)
	v_mfma_f32_16x16x32_bf16 v[28:31], v[64:67], v[188:191], v[28:31]
	v_mfma_f32_16x16x32_bf16 v[60:63], v[68:71], v[188:191], v[60:63]
	v_mfma_f32_16x16x32_bf16 v[248:251], v[72:75], v[188:191], v[248:251]
	v_mfma_f32_16x16x32_bf16 v[124:127], v[76:79], v[188:191], v[124:127]
	s_waitcnt vmcnt(8)
	ds_read_b128 v[188:191], v212 offset:45056
	global_load_dwordx4 v[64:67], v142, s[84:85] offset:0
	s_waitcnt lgkmcnt(6)
	v_mfma_f32_16x16x32_bf16 v[0:3], v[80:83], v[192:195], v[0:3]
	v_mfma_f32_16x16x32_bf16 v[32:35], v[84:87], v[192:195], v[32:35]
	v_mfma_f32_16x16x32_bf16 v[144:147], v[88:91], v[192:195], v[144:147]
	v_mfma_f32_16x16x32_bf16 v[252:255], v[92:95], v[192:195], v[252:255]
	ds_read_b128 v[192:195], v212 offset:47104
	global_load_dwordx4 v[68:71], v150, s[84:85] offset:0
	s_waitcnt lgkmcnt(6)
	v_mfma_f32_16x16x32_bf16 v[4:7], v[80:83], v[196:199], v[4:7]
	v_mfma_f32_16x16x32_bf16 v[36:39], v[84:87], v[196:199], v[36:39]
	v_mfma_f32_16x16x32_bf16 v[184:187], v[88:91], v[196:199], v[184:187]
	v_mfma_f32_16x16x32_bf16 v[100:103], v[92:95], v[196:199], v[100:103]
	ds_read_b128 v[196:199], v213 offset:32768
	global_load_dwordx4 v[72:75], v142, s[92:93] offset:0
	s_waitcnt lgkmcnt(6)
	v_mfma_f32_16x16x32_bf16 v[8:11], v[80:83], v[200:203], v[8:11]
	v_mfma_f32_16x16x32_bf16 v[40:43], v[84:87], v[200:203], v[40:43]
	v_mfma_f32_16x16x32_bf16 v[204:207], v[88:91], v[200:203], v[204:207]
	v_mfma_f32_16x16x32_bf16 v[104:107], v[92:95], v[200:203], v[104:107]
	ds_read_b128 v[200:203], v213 offset:34816
	global_load_dwordx4 v[76:79], v150, s[92:93] offset:0
	s_waitcnt lgkmcnt(6)
	v_mfma_f32_16x16x32_bf16 v[12:15], v[80:83], v[160:163], v[12:15]
	v_mfma_f32_16x16x32_bf16 v[44:47], v[84:87], v[160:163], v[44:47]
	v_mfma_f32_16x16x32_bf16 v[208:211], v[88:91], v[160:163], v[208:211]
	v_mfma_f32_16x16x32_bf16 v[108:111], v[92:95], v[160:163], v[108:111]
	ds_read_b128 v[160:163], v213 offset:36864
	s_waitcnt lgkmcnt(6)
	v_mfma_f32_16x16x32_bf16 v[16:19], v[80:83], v[176:179], v[16:19]
	v_mfma_f32_16x16x32_bf16 v[48:51], v[84:87], v[176:179], v[48:51]
	v_mfma_f32_16x16x32_bf16 v[232:235], v[88:91], v[176:179], v[232:235]
	v_mfma_f32_16x16x32_bf16 v[112:115], v[92:95], v[176:179], v[112:115]
	ds_read_b128 v[176:179], v213 offset:38912
	s_waitcnt lgkmcnt(6)
	v_mfma_f32_16x16x32_bf16 v[20:23], v[80:83], v[180:183], v[20:23]
	v_mfma_f32_16x16x32_bf16 v[52:55], v[84:87], v[180:183], v[52:55]
	v_mfma_f32_16x16x32_bf16 v[236:239], v[88:91], v[180:183], v[236:239]
	v_mfma_f32_16x16x32_bf16 v[116:119], v[92:95], v[180:183], v[116:119]
	ds_read_b128 v[180:183], v213 offset:40960
	s_waitcnt lgkmcnt(6)
	v_mfma_f32_16x16x32_bf16 v[24:27], v[80:83], v[188:191], v[24:27]
	v_mfma_f32_16x16x32_bf16 v[56:59], v[84:87], v[188:191], v[56:59]
	v_mfma_f32_16x16x32_bf16 v[240:243], v[88:91], v[188:191], v[240:243]
	v_mfma_f32_16x16x32_bf16 v[120:123], v[92:95], v[188:191], v[120:123]
	ds_read_b128 v[188:191], v213 offset:43008
	s_waitcnt lgkmcnt(6)
	v_mfma_f32_16x16x32_bf16 v[28:31], v[80:83], v[192:195], v[28:31]
	v_mfma_f32_16x16x32_bf16 v[60:63], v[84:87], v[192:195], v[60:63]
	v_mfma_f32_16x16x32_bf16 v[248:251], v[88:91], v[192:195], v[248:251]
	v_mfma_f32_16x16x32_bf16 v[124:127], v[92:95], v[192:195], v[124:127]
	s_waitcnt vmcnt(16)
	s_barrier
	s_waitcnt vmcnt(8)
	ds_read_b128 v[192:195], v213 offset:45056
	global_load_dwordx4 v[80:83], v142, s[84:85] offset:1024
	s_waitcnt lgkmcnt(6)
	v_mfma_f32_16x16x32_bf16 v[0:3], v[96:99], v[196:199], v[0:3]
	v_mfma_f32_16x16x32_bf16 v[32:35], v[164:167], v[196:199], v[32:35]
	v_mfma_f32_16x16x32_bf16 v[144:147], v[168:171], v[196:199], v[144:147]
	v_mfma_f32_16x16x32_bf16 v[252:255], v[172:175], v[196:199], v[252:255]
	ds_read_b128 v[196:199], v213 offset:47104
	global_load_dwordx4 v[84:87], v150, s[84:85] offset:1024
	s_waitcnt lgkmcnt(6)
	v_mfma_f32_16x16x32_bf16 v[4:7], v[96:99], v[200:203], v[4:7]
	v_mfma_f32_16x16x32_bf16 v[36:39], v[164:167], v[200:203], v[36:39]
	v_mfma_f32_16x16x32_bf16 v[184:187], v[168:171], v[200:203], v[184:187]
	v_mfma_f32_16x16x32_bf16 v[100:103], v[172:175], v[200:203], v[100:103]
	ds_read_b128 v[200:203], v212 offset:49152
	global_load_dwordx4 v[88:91], v142, s[92:93] offset:1024
	s_waitcnt lgkmcnt(6)
	v_mfma_f32_16x16x32_bf16 v[8:11], v[96:99], v[160:163], v[8:11]
	v_mfma_f32_16x16x32_bf16 v[40:43], v[164:167], v[160:163], v[40:43]
	v_mfma_f32_16x16x32_bf16 v[204:207], v[168:171], v[160:163], v[204:207]
	v_mfma_f32_16x16x32_bf16 v[104:107], v[172:175], v[160:163], v[104:107]
	ds_read_b128 v[160:163], v212 offset:51200
	global_load_dwordx4 v[92:95], v150, s[92:93] offset:1024
	s_add_u32 s84, s84, 0x800
	s_addc_u32 s85, s85, 0
	s_add_u32 s92, s92, 0x800
	s_addc_u32 s93, s93, 0
	s_waitcnt lgkmcnt(6)
	v_mfma_f32_16x16x32_bf16 v[12:15], v[96:99], v[176:179], v[12:15]
	v_mfma_f32_16x16x32_bf16 v[44:47], v[164:167], v[176:179], v[44:47]
	v_mfma_f32_16x16x32_bf16 v[208:211], v[168:171], v[176:179], v[208:211]
	v_mfma_f32_16x16x32_bf16 v[108:111], v[172:175], v[176:179], v[108:111]
	ds_read_b128 v[176:179], v212 offset:53248
	s_add_u32 m0, s1, 16384
	s_nop 0
	global_load_lds_dwordx4 v151, s[86:87]
	s_waitcnt lgkmcnt(6)
	v_mfma_f32_16x16x32_bf16 v[16:19], v[96:99], v[180:183], v[16:19]
	v_mfma_f32_16x16x32_bf16 v[48:51], v[164:167], v[180:183], v[48:51]
	v_mfma_f32_16x16x32_bf16 v[232:235], v[168:171], v[180:183], v[232:235]
	v_mfma_f32_16x16x32_bf16 v[112:115], v[172:175], v[180:183], v[112:115]
	ds_read_b128 v[180:183], v212 offset:55296
	s_add_u32 m0, s1, 20480
	s_nop 0
	global_load_lds_dwordx4 v156, s[86:87]
	s_waitcnt lgkmcnt(6)
	v_mfma_f32_16x16x32_bf16 v[20:23], v[96:99], v[188:191], v[20:23]
	v_mfma_f32_16x16x32_bf16 v[52:55], v[164:167], v[188:191], v[52:55]
	v_mfma_f32_16x16x32_bf16 v[236:239], v[168:171], v[188:191], v[236:239]
	v_mfma_f32_16x16x32_bf16 v[116:119], v[172:175], v[188:191], v[116:119]
	ds_read_b128 v[188:191], v212 offset:57344
	s_add_u32 m0, s1, 24576
	s_nop 0
	global_load_lds_dwordx4 v158, s[86:87]
	s_waitcnt lgkmcnt(6)
	v_mfma_f32_16x16x32_bf16 v[24:27], v[96:99], v[192:195], v[24:27]
	v_mfma_f32_16x16x32_bf16 v[56:59], v[164:167], v[192:195], v[56:59]
	v_mfma_f32_16x16x32_bf16 v[240:243], v[168:171], v[192:195], v[240:243]
	v_mfma_f32_16x16x32_bf16 v[120:123], v[172:175], v[192:195], v[120:123]
	ds_read_b128 v[192:195], v212 offset:59392
	s_add_u32 m0, s1, 28672
	s_nop 0
	global_load_lds_dwordx4 v159, s[86:87]
	s_add_u32 s86, s86, 128
	s_addc_u32 s87, s87, 0
	s_waitcnt lgkmcnt(6)
	v_mfma_f32_16x16x32_bf16 v[28:31], v[96:99], v[196:199], v[28:31]
	v_mfma_f32_16x16x32_bf16 v[60:63], v[164:167], v[196:199], v[60:63]
	v_mfma_f32_16x16x32_bf16 v[248:251], v[168:171], v[196:199], v[248:251]
	v_mfma_f32_16x16x32_bf16 v[124:127], v[172:175], v[196:199], v[124:127]
	s_waitcnt vmcnt(8)
	ds_read_b128 v[196:199], v212 offset:61440
	global_load_dwordx4 v[96:99], v142, s[84:85] offset:0
	s_waitcnt lgkmcnt(6)
	v_mfma_f32_16x16x32_bf16 v[0:3], v[64:67], v[200:203], v[0:3]
	v_mfma_f32_16x16x32_bf16 v[32:35], v[68:71], v[200:203], v[32:35]
	v_mfma_f32_16x16x32_bf16 v[144:147], v[72:75], v[200:203], v[144:147]
	v_mfma_f32_16x16x32_bf16 v[252:255], v[76:79], v[200:203], v[252:255]
	ds_read_b128 v[200:203], v212 offset:63488
	global_load_dwordx4 v[164:167], v150, s[84:85] offset:0
	s_waitcnt lgkmcnt(6)
	v_mfma_f32_16x16x32_bf16 v[4:7], v[64:67], v[160:163], v[4:7]
	v_mfma_f32_16x16x32_bf16 v[36:39], v[68:71], v[160:163], v[36:39]
	v_mfma_f32_16x16x32_bf16 v[184:187], v[72:75], v[160:163], v[184:187]
	v_mfma_f32_16x16x32_bf16 v[100:103], v[76:79], v[160:163], v[100:103]
	ds_read_b128 v[160:163], v213 offset:49152
	global_load_dwordx4 v[168:171], v142, s[92:93] offset:0
	s_waitcnt lgkmcnt(6)
	v_mfma_f32_16x16x32_bf16 v[8:11], v[64:67], v[176:179], v[8:11]
	v_mfma_f32_16x16x32_bf16 v[40:43], v[68:71], v[176:179], v[40:43]
	v_mfma_f32_16x16x32_bf16 v[204:207], v[72:75], v[176:179], v[204:207]
	v_mfma_f32_16x16x32_bf16 v[104:107], v[76:79], v[176:179], v[104:107]
	ds_read_b128 v[176:179], v213 offset:51200
	global_load_dwordx4 v[172:175], v150, s[92:93] offset:0
	s_waitcnt lgkmcnt(6)
	v_mfma_f32_16x16x32_bf16 v[12:15], v[64:67], v[180:183], v[12:15]
	v_mfma_f32_16x16x32_bf16 v[44:47], v[68:71], v[180:183], v[44:47]
	v_mfma_f32_16x16x32_bf16 v[208:211], v[72:75], v[180:183], v[208:211]
	v_mfma_f32_16x16x32_bf16 v[108:111], v[76:79], v[180:183], v[108:111]
	ds_read_b128 v[180:183], v213 offset:53248
	s_waitcnt lgkmcnt(6)
	v_mfma_f32_16x16x32_bf16 v[16:19], v[64:67], v[188:191], v[16:19]
	v_mfma_f32_16x16x32_bf16 v[48:51], v[68:71], v[188:191], v[48:51]
	v_mfma_f32_16x16x32_bf16 v[232:235], v[72:75], v[188:191], v[232:235]
	v_mfma_f32_16x16x32_bf16 v[112:115], v[76:79], v[188:191], v[112:115]
	ds_read_b128 v[188:191], v213 offset:55296
	s_waitcnt lgkmcnt(6)
	v_mfma_f32_16x16x32_bf16 v[20:23], v[64:67], v[192:195], v[20:23]
	v_mfma_f32_16x16x32_bf16 v[52:55], v[68:71], v[192:195], v[52:55]
	v_mfma_f32_16x16x32_bf16 v[236:239], v[72:75], v[192:195], v[236:239]
	v_mfma_f32_16x16x32_bf16 v[116:119], v[76:79], v[192:195], v[116:119]
	ds_read_b128 v[192:195], v213 offset:57344
	s_waitcnt lgkmcnt(6)
	v_mfma_f32_16x16x32_bf16 v[24:27], v[64:67], v[196:199], v[24:27]
	v_mfma_f32_16x16x32_bf16 v[56:59], v[68:71], v[196:199], v[56:59]
	v_mfma_f32_16x16x32_bf16 v[240:243], v[72:75], v[196:199], v[240:243]
	v_mfma_f32_16x16x32_bf16 v[120:123], v[76:79], v[196:199], v[120:123]
	ds_read_b128 v[196:199], v213 offset:59392
	s_waitcnt lgkmcnt(6)
	v_mfma_f32_16x16x32_bf16 v[28:31], v[64:67], v[200:203], v[28:31]
	v_mfma_f32_16x16x32_bf16 v[60:63], v[68:71], v[200:203], v[60:63]
	v_mfma_f32_16x16x32_bf16 v[248:251], v[72:75], v[200:203], v[248:251]
	v_mfma_f32_16x16x32_bf16 v[124:127], v[76:79], v[200:203], v[124:127]
	s_waitcnt vmcnt(16)
	s_barrier
	s_waitcnt vmcnt(8)
	ds_read_b128 v[200:203], v213 offset:61440
	global_load_dwordx4 v[64:67], v142, s[84:85] offset:1024
	s_waitcnt lgkmcnt(6)
	v_mfma_f32_16x16x32_bf16 v[0:3], v[80:83], v[160:163], v[0:3]
	v_mfma_f32_16x16x32_bf16 v[32:35], v[84:87], v[160:163], v[32:35]
	v_mfma_f32_16x16x32_bf16 v[144:147], v[88:91], v[160:163], v[144:147]
	v_mfma_f32_16x16x32_bf16 v[252:255], v[92:95], v[160:163], v[252:255]
	ds_read_b128 v[160:163], v213 offset:63488
	global_load_dwordx4 v[68:71], v150, s[84:85] offset:1024
	s_waitcnt lgkmcnt(6)
	v_mfma_f32_16x16x32_bf16 v[4:7], v[80:83], v[176:179], v[4:7]
	v_mfma_f32_16x16x32_bf16 v[36:39], v[84:87], v[176:179], v[36:39]
	v_mfma_f32_16x16x32_bf16 v[184:187], v[88:91], v[176:179], v[184:187]
	v_mfma_f32_16x16x32_bf16 v[100:103], v[92:95], v[176:179], v[100:103]
	ds_read_b128 v[176:179], v212 offset:0
	global_load_dwordx4 v[72:75], v142, s[92:93] offset:1024
	s_waitcnt lgkmcnt(6)
	v_mfma_f32_16x16x32_bf16 v[8:11], v[80:83], v[180:183], v[8:11]
	v_mfma_f32_16x16x32_bf16 v[40:43], v[84:87], v[180:183], v[40:43]
	v_mfma_f32_16x16x32_bf16 v[204:207], v[88:91], v[180:183], v[204:207]
	v_mfma_f32_16x16x32_bf16 v[104:107], v[92:95], v[180:183], v[104:107]
	ds_read_b128 v[180:183], v212 offset:2048
	global_load_dwordx4 v[76:79], v150, s[92:93] offset:1024
	s_add_u32 s84, s84, 0x800
	s_addc_u32 s85, s85, 0
	s_add_u32 s92, s92, 0x800
	s_addc_u32 s93, s93, 0
	s_waitcnt lgkmcnt(6)
	v_mfma_f32_16x16x32_bf16 v[12:15], v[80:83], v[188:191], v[12:15]
	v_mfma_f32_16x16x32_bf16 v[44:47], v[84:87], v[188:191], v[44:47]
	v_mfma_f32_16x16x32_bf16 v[208:211], v[88:91], v[188:191], v[208:211]
	v_mfma_f32_16x16x32_bf16 v[108:111], v[92:95], v[188:191], v[108:111]
	ds_read_b128 v[188:191], v212 offset:4096
	s_add_u32 m0, s1, 32768
	s_nop 0
	global_load_lds_dwordx4 v151, s[86:87]
	s_waitcnt lgkmcnt(6)
	v_mfma_f32_16x16x32_bf16 v[16:19], v[80:83], v[192:195], v[16:19]
	v_mfma_f32_16x16x32_bf16 v[48:51], v[84:87], v[192:195], v[48:51]
	v_mfma_f32_16x16x32_bf16 v[232:235], v[88:91], v[192:195], v[232:235]
	v_mfma_f32_16x16x32_bf16 v[112:115], v[92:95], v[192:195], v[112:115]
	ds_read_b128 v[192:195], v212 offset:6144
	s_add_u32 m0, s1, 36864
	s_nop 0
	global_load_lds_dwordx4 v156, s[86:87]
	s_waitcnt lgkmcnt(6)
	v_mfma_f32_16x16x32_bf16 v[20:23], v[80:83], v[196:199], v[20:23]
	v_mfma_f32_16x16x32_bf16 v[52:55], v[84:87], v[196:199], v[52:55]
	v_mfma_f32_16x16x32_bf16 v[236:239], v[88:91], v[196:199], v[236:239]
	v_mfma_f32_16x16x32_bf16 v[116:119], v[92:95], v[196:199], v[116:119]
	ds_read_b128 v[196:199], v212 offset:8192
	s_add_u32 m0, s1, 40960
	s_nop 0
	global_load_lds_dwordx4 v158, s[86:87]
	s_waitcnt lgkmcnt(6)
	v_mfma_f32_16x16x32_bf16 v[24:27], v[80:83], v[200:203], v[24:27]
	v_mfma_f32_16x16x32_bf16 v[56:59], v[84:87], v[200:203], v[56:59]
	v_mfma_f32_16x16x32_bf16 v[240:243], v[88:91], v[200:203], v[240:243]
	v_mfma_f32_16x16x32_bf16 v[120:123], v[92:95], v[200:203], v[120:123]
	ds_read_b128 v[200:203], v212 offset:10240
	s_add_u32 m0, s1, 45056
	s_nop 0
	global_load_lds_dwordx4 v159, s[86:87]
	s_add_u32 s86, s86, 128
	s_addc_u32 s87, s87, 0
	s_waitcnt lgkmcnt(6)
	v_mfma_f32_16x16x32_bf16 v[28:31], v[80:83], v[160:163], v[28:31]
	v_mfma_f32_16x16x32_bf16 v[60:63], v[84:87], v[160:163], v[60:63]
	v_mfma_f32_16x16x32_bf16 v[248:251], v[88:91], v[160:163], v[248:251]
	v_mfma_f32_16x16x32_bf16 v[124:127], v[92:95], v[160:163], v[124:127]
	s_waitcnt vmcnt(8)
	ds_read_b128 v[160:163], v212 offset:12288
	global_load_dwordx4 v[80:83], v142, s[84:85] offset:0
	s_waitcnt lgkmcnt(6)
	v_mfma_f32_16x16x32_bf16 v[0:3], v[96:99], v[176:179], v[0:3]
	v_mfma_f32_16x16x32_bf16 v[32:35], v[164:167], v[176:179], v[32:35]
	v_mfma_f32_16x16x32_bf16 v[144:147], v[168:171], v[176:179], v[144:147]
	v_mfma_f32_16x16x32_bf16 v[252:255], v[172:175], v[176:179], v[252:255]
	ds_read_b128 v[176:179], v212 offset:14336
	global_load_dwordx4 v[84:87], v150, s[84:85] offset:0
	s_waitcnt lgkmcnt(6)
	v_mfma_f32_16x16x32_bf16 v[4:7], v[96:99], v[180:183], v[4:7]
	v_mfma_f32_16x16x32_bf16 v[36:39], v[164:167], v[180:183], v[36:39]
	v_mfma_f32_16x16x32_bf16 v[184:187], v[168:171], v[180:183], v[184:187]
	v_mfma_f32_16x16x32_bf16 v[100:103], v[172:175], v[180:183], v[100:103]
	ds_read_b128 v[180:183], v213 offset:0
	global_load_dwordx4 v[88:91], v142, s[92:93] offset:0
	s_waitcnt lgkmcnt(6)
	v_mfma_f32_16x16x32_bf16 v[8:11], v[96:99], v[188:191], v[8:11]
	v_mfma_f32_16x16x32_bf16 v[40:43], v[164:167], v[188:191], v[40:43]
	v_mfma_f32_16x16x32_bf16 v[204:207], v[168:171], v[188:191], v[204:207]
	v_mfma_f32_16x16x32_bf16 v[104:107], v[172:175], v[188:191], v[104:107]
	ds_read_b128 v[188:191], v213 offset:2048
	global_load_dwordx4 v[92:95], v150, s[92:93] offset:0
	s_waitcnt lgkmcnt(6)
	v_mfma_f32_16x16x32_bf16 v[12:15], v[96:99], v[192:195], v[12:15]
	v_mfma_f32_16x16x32_bf16 v[44:47], v[164:167], v[192:195], v[44:47]
	v_mfma_f32_16x16x32_bf16 v[208:211], v[168:171], v[192:195], v[208:211]
	v_mfma_f32_16x16x32_bf16 v[108:111], v[172:175], v[192:195], v[108:111]
	ds_read_b128 v[192:195], v213 offset:4096
	s_waitcnt lgkmcnt(6)
	v_mfma_f32_16x16x32_bf16 v[16:19], v[96:99], v[196:199], v[16:19]
	v_mfma_f32_16x16x32_bf16 v[48:51], v[164:167], v[196:199], v[48:51]
	v_mfma_f32_16x16x32_bf16 v[232:235], v[168:171], v[196:199], v[232:235]
	v_mfma_f32_16x16x32_bf16 v[112:115], v[172:175], v[196:199], v[112:115]
	ds_read_b128 v[196:199], v213 offset:6144
	s_waitcnt lgkmcnt(6)
	v_mfma_f32_16x16x32_bf16 v[20:23], v[96:99], v[200:203], v[20:23]
	v_mfma_f32_16x16x32_bf16 v[52:55], v[164:167], v[200:203], v[52:55]
	v_mfma_f32_16x16x32_bf16 v[236:239], v[168:171], v[200:203], v[236:239]
	v_mfma_f32_16x16x32_bf16 v[116:119], v[172:175], v[200:203], v[116:119]
	ds_read_b128 v[200:203], v213 offset:8192
	s_waitcnt lgkmcnt(6)
	v_mfma_f32_16x16x32_bf16 v[24:27], v[96:99], v[160:163], v[24:27]
	v_mfma_f32_16x16x32_bf16 v[56:59], v[164:167], v[160:163], v[56:59]
	v_mfma_f32_16x16x32_bf16 v[240:243], v[168:171], v[160:163], v[240:243]
	v_mfma_f32_16x16x32_bf16 v[120:123], v[172:175], v[160:163], v[120:123]
	ds_read_b128 v[160:163], v213 offset:10240
	s_waitcnt lgkmcnt(6)
	v_mfma_f32_16x16x32_bf16 v[28:31], v[96:99], v[176:179], v[28:31]
	v_mfma_f32_16x16x32_bf16 v[60:63], v[164:167], v[176:179], v[60:63]
	v_mfma_f32_16x16x32_bf16 v[248:251], v[168:171], v[176:179], v[248:251]
	v_mfma_f32_16x16x32_bf16 v[124:127], v[172:175], v[176:179], v[124:127]
	s_waitcnt vmcnt(16)
	s_barrier
	s_waitcnt vmcnt(8)
	ds_read_b128 v[176:179], v213 offset:12288
	global_load_dwordx4 v[96:99], v142, s[84:85] offset:1024
	s_waitcnt lgkmcnt(6)
	v_mfma_f32_16x16x32_bf16 v[0:3], v[64:67], v[180:183], v[0:3]
	v_mfma_f32_16x16x32_bf16 v[32:35], v[68:71], v[180:183], v[32:35]
	v_mfma_f32_16x16x32_bf16 v[144:147], v[72:75], v[180:183], v[144:147]
	v_mfma_f32_16x16x32_bf16 v[252:255], v[76:79], v[180:183], v[252:255]
	ds_read_b128 v[180:183], v213 offset:14336
	global_load_dwordx4 v[164:167], v150, s[84:85] offset:1024
	s_waitcnt lgkmcnt(6)
	v_mfma_f32_16x16x32_bf16 v[4:7], v[64:67], v[188:191], v[4:7]
	v_mfma_f32_16x16x32_bf16 v[36:39], v[68:71], v[188:191], v[36:39]
	v_mfma_f32_16x16x32_bf16 v[184:187], v[72:75], v[188:191], v[184:187]
	v_mfma_f32_16x16x32_bf16 v[100:103], v[76:79], v[188:191], v[100:103]
	ds_read_b128 v[188:191], v212 offset:16384
	global_load_dwordx4 v[168:171], v142, s[92:93] offset:1024
	s_waitcnt lgkmcnt(6)
	v_mfma_f32_16x16x32_bf16 v[8:11], v[64:67], v[192:195], v[8:11]
	v_mfma_f32_16x16x32_bf16 v[40:43], v[68:71], v[192:195], v[40:43]
	v_mfma_f32_16x16x32_bf16 v[204:207], v[72:75], v[192:195], v[204:207]
	v_mfma_f32_16x16x32_bf16 v[104:107], v[76:79], v[192:195], v[104:107]
	ds_read_b128 v[192:195], v212 offset:18432
	global_load_dwordx4 v[172:175], v150, s[92:93] offset:1024
	s_add_u32 s84, s84, 0x800
	s_addc_u32 s85, s85, 0
	s_add_u32 s92, s92, 0x800
	s_addc_u32 s93, s93, 0
	s_waitcnt lgkmcnt(6)
	v_mfma_f32_16x16x32_bf16 v[12:15], v[64:67], v[196:199], v[12:15]
	v_mfma_f32_16x16x32_bf16 v[44:47], v[68:71], v[196:199], v[44:47]
	v_mfma_f32_16x16x32_bf16 v[208:211], v[72:75], v[196:199], v[208:211]
	v_mfma_f32_16x16x32_bf16 v[108:111], v[76:79], v[196:199], v[108:111]
	ds_read_b128 v[196:199], v212 offset:20480
	s_add_u32 m0, s1, 49152
	s_nop 0
	global_load_lds_dwordx4 v151, s[86:87]
	s_waitcnt lgkmcnt(6)
	v_mfma_f32_16x16x32_bf16 v[16:19], v[64:67], v[200:203], v[16:19]
	v_mfma_f32_16x16x32_bf16 v[48:51], v[68:71], v[200:203], v[48:51]
	v_mfma_f32_16x16x32_bf16 v[232:235], v[72:75], v[200:203], v[232:235]
	v_mfma_f32_16x16x32_bf16 v[112:115], v[76:79], v[200:203], v[112:115]
	ds_read_b128 v[200:203], v212 offset:22528
	s_add_u32 m0, s1, 53248
	s_nop 0
	global_load_lds_dwordx4 v156, s[86:87]
	s_waitcnt lgkmcnt(6)
	v_mfma_f32_16x16x32_bf16 v[20:23], v[64:67], v[160:163], v[20:23]
	v_mfma_f32_16x16x32_bf16 v[52:55], v[68:71], v[160:163], v[52:55]
	v_mfma_f32_16x16x32_bf16 v[236:239], v[72:75], v[160:163], v[236:239]
	v_mfma_f32_16x16x32_bf16 v[116:119], v[76:79], v[160:163], v[116:119]
	ds_read_b128 v[160:163], v212 offset:24576
	s_add_u32 m0, s1, 57344
	s_nop 0
	global_load_lds_dwordx4 v158, s[86:87]
	s_waitcnt lgkmcnt(6)
	v_mfma_f32_16x16x32_bf16 v[24:27], v[64:67], v[176:179], v[24:27]
	v_mfma_f32_16x16x32_bf16 v[56:59], v[68:71], v[176:179], v[56:59]
	v_mfma_f32_16x16x32_bf16 v[240:243], v[72:75], v[176:179], v[240:243]
	v_mfma_f32_16x16x32_bf16 v[120:123], v[76:79], v[176:179], v[120:123]
	ds_read_b128 v[176:179], v212 offset:26624
	s_add_u32 m0, s1, 61440
	s_nop 0
	global_load_lds_dwordx4 v159, s[86:87]
	s_add_u32 s86, s86, 128
	s_addc_u32 s87, s87, 0
	s_waitcnt lgkmcnt(6)
	v_mfma_f32_16x16x32_bf16 v[28:31], v[64:67], v[180:183], v[28:31]
	v_mfma_f32_16x16x32_bf16 v[60:63], v[68:71], v[180:183], v[60:63]
	v_mfma_f32_16x16x32_bf16 v[248:251], v[72:75], v[180:183], v[248:251]
	v_mfma_f32_16x16x32_bf16 v[124:127], v[76:79], v[180:183], v[124:127]
	s_waitcnt vmcnt(8)
	ds_read_b128 v[180:183], v212 offset:28672
	global_load_dwordx4 v[64:67], v142, s[84:85] offset:0
	s_waitcnt lgkmcnt(6)
	v_mfma_f32_16x16x32_bf16 v[0:3], v[80:83], v[188:191], v[0:3]
	v_mfma_f32_16x16x32_bf16 v[32:35], v[84:87], v[188:191], v[32:35]
	v_mfma_f32_16x16x32_bf16 v[144:147], v[88:91], v[188:191], v[144:147]
	v_mfma_f32_16x16x32_bf16 v[252:255], v[92:95], v[188:191], v[252:255]
	ds_read_b128 v[188:191], v212 offset:30720
	global_load_dwordx4 v[68:71], v150, s[84:85] offset:0
	s_waitcnt lgkmcnt(6)
	v_mfma_f32_16x16x32_bf16 v[4:7], v[80:83], v[192:195], v[4:7]
	v_mfma_f32_16x16x32_bf16 v[36:39], v[84:87], v[192:195], v[36:39]
	v_mfma_f32_16x16x32_bf16 v[184:187], v[88:91], v[192:195], v[184:187]
	v_mfma_f32_16x16x32_bf16 v[100:103], v[92:95], v[192:195], v[100:103]
	ds_read_b128 v[192:195], v213 offset:16384
	global_load_dwordx4 v[72:75], v142, s[92:93] offset:0
	s_waitcnt lgkmcnt(6)
	v_mfma_f32_16x16x32_bf16 v[8:11], v[80:83], v[196:199], v[8:11]
	v_mfma_f32_16x16x32_bf16 v[40:43], v[84:87], v[196:199], v[40:43]
	v_mfma_f32_16x16x32_bf16 v[204:207], v[88:91], v[196:199], v[204:207]
	v_mfma_f32_16x16x32_bf16 v[104:107], v[92:95], v[196:199], v[104:107]
	ds_read_b128 v[196:199], v213 offset:18432
	global_load_dwordx4 v[76:79], v150, s[92:93] offset:0
	s_waitcnt lgkmcnt(6)
	v_mfma_f32_16x16x32_bf16 v[12:15], v[80:83], v[200:203], v[12:15]
	v_mfma_f32_16x16x32_bf16 v[44:47], v[84:87], v[200:203], v[44:47]
	v_mfma_f32_16x16x32_bf16 v[208:211], v[88:91], v[200:203], v[208:211]
	v_mfma_f32_16x16x32_bf16 v[108:111], v[92:95], v[200:203], v[108:111]
	ds_read_b128 v[200:203], v213 offset:20480
	s_waitcnt lgkmcnt(6)
	v_mfma_f32_16x16x32_bf16 v[16:19], v[80:83], v[160:163], v[16:19]
	v_mfma_f32_16x16x32_bf16 v[48:51], v[84:87], v[160:163], v[48:51]
	v_mfma_f32_16x16x32_bf16 v[232:235], v[88:91], v[160:163], v[232:235]
	v_mfma_f32_16x16x32_bf16 v[112:115], v[92:95], v[160:163], v[112:115]
	ds_read_b128 v[160:163], v213 offset:22528
	s_waitcnt lgkmcnt(6)
	v_mfma_f32_16x16x32_bf16 v[20:23], v[80:83], v[176:179], v[20:23]
	v_mfma_f32_16x16x32_bf16 v[52:55], v[84:87], v[176:179], v[52:55]
	v_mfma_f32_16x16x32_bf16 v[236:239], v[88:91], v[176:179], v[236:239]
	v_mfma_f32_16x16x32_bf16 v[116:119], v[92:95], v[176:179], v[116:119]
	ds_read_b128 v[176:179], v213 offset:24576
	s_waitcnt lgkmcnt(6)
	v_mfma_f32_16x16x32_bf16 v[24:27], v[80:83], v[180:183], v[24:27]
	v_mfma_f32_16x16x32_bf16 v[56:59], v[84:87], v[180:183], v[56:59]
	v_mfma_f32_16x16x32_bf16 v[240:243], v[88:91], v[180:183], v[240:243]
	v_mfma_f32_16x16x32_bf16 v[120:123], v[92:95], v[180:183], v[120:123]
	ds_read_b128 v[180:183], v213 offset:26624
	s_waitcnt lgkmcnt(6)
	v_mfma_f32_16x16x32_bf16 v[28:31], v[80:83], v[188:191], v[28:31]
	v_mfma_f32_16x16x32_bf16 v[60:63], v[84:87], v[188:191], v[60:63]
	v_mfma_f32_16x16x32_bf16 v[248:251], v[88:91], v[188:191], v[248:251]
	v_mfma_f32_16x16x32_bf16 v[124:127], v[92:95], v[188:191], v[124:127]
	s_waitcnt vmcnt(16)
	s_barrier
	s_waitcnt vmcnt(8)
	ds_read_b128 v[188:191], v213 offset:28672
	global_load_dwordx4 v[80:83], v142, s[84:85] offset:1024
	s_waitcnt lgkmcnt(6)
	v_mfma_f32_16x16x32_bf16 v[0:3], v[96:99], v[192:195], v[0:3]
	v_mfma_f32_16x16x32_bf16 v[32:35], v[164:167], v[192:195], v[32:35]
	v_mfma_f32_16x16x32_bf16 v[144:147], v[168:171], v[192:195], v[144:147]
	v_mfma_f32_16x16x32_bf16 v[252:255], v[172:175], v[192:195], v[252:255]
	ds_read_b128 v[192:195], v213 offset:30720
	global_load_dwordx4 v[84:87], v150, s[84:85] offset:1024
	s_waitcnt lgkmcnt(6)
	v_mfma_f32_16x16x32_bf16 v[4:7], v[96:99], v[196:199], v[4:7]
	v_mfma_f32_16x16x32_bf16 v[36:39], v[164:167], v[196:199], v[36:39]
	v_mfma_f32_16x16x32_bf16 v[184:187], v[168:171], v[196:199], v[184:187]
	v_mfma_f32_16x16x32_bf16 v[100:103], v[172:175], v[196:199], v[100:103]
	ds_read_b128 v[196:199], v212 offset:32768
	global_load_dwordx4 v[88:91], v142, s[92:93] offset:1024
	s_waitcnt lgkmcnt(6)
	v_mfma_f32_16x16x32_bf16 v[8:11], v[96:99], v[200:203], v[8:11]
	v_mfma_f32_16x16x32_bf16 v[40:43], v[164:167], v[200:203], v[40:43]
	v_mfma_f32_16x16x32_bf16 v[204:207], v[168:171], v[200:203], v[204:207]
	v_mfma_f32_16x16x32_bf16 v[104:107], v[172:175], v[200:203], v[104:107]
	ds_read_b128 v[200:203], v212 offset:34816
	global_load_dwordx4 v[92:95], v150, s[92:93] offset:1024
	s_add_u32 s84, s84, 0x800
	s_addc_u32 s85, s85, 0
	s_add_u32 s92, s92, 0x800
	s_addc_u32 s93, s93, 0
	s_waitcnt lgkmcnt(6)
	v_mfma_f32_16x16x32_bf16 v[12:15], v[96:99], v[160:163], v[12:15]
	v_mfma_f32_16x16x32_bf16 v[44:47], v[164:167], v[160:163], v[44:47]
	v_mfma_f32_16x16x32_bf16 v[208:211], v[168:171], v[160:163], v[208:211]
	v_mfma_f32_16x16x32_bf16 v[108:111], v[172:175], v[160:163], v[108:111]
	ds_read_b128 v[160:163], v212 offset:36864
	s_add_u32 m0, s1, 0
	s_nop 0
	global_load_lds_dwordx4 v151, s[86:87]
	s_waitcnt lgkmcnt(6)
	v_mfma_f32_16x16x32_bf16 v[16:19], v[96:99], v[176:179], v[16:19]
	v_mfma_f32_16x16x32_bf16 v[48:51], v[164:167], v[176:179], v[48:51]
	v_mfma_f32_16x16x32_bf16 v[232:235], v[168:171], v[176:179], v[232:235]
	v_mfma_f32_16x16x32_bf16 v[112:115], v[172:175], v[176:179], v[112:115]
	ds_read_b128 v[176:179], v212 offset:38912
	s_add_u32 m0, s1, 4096
	s_nop 0
	global_load_lds_dwordx4 v156, s[86:87]
	s_waitcnt lgkmcnt(6)
	v_mfma_f32_16x16x32_bf16 v[20:23], v[96:99], v[180:183], v[20:23]
	v_mfma_f32_16x16x32_bf16 v[52:55], v[164:167], v[180:183], v[52:55]
	v_mfma_f32_16x16x32_bf16 v[236:239], v[168:171], v[180:183], v[236:239]
	v_mfma_f32_16x16x32_bf16 v[116:119], v[172:175], v[180:183], v[116:119]
	ds_read_b128 v[180:183], v212 offset:40960
	s_add_u32 m0, s1, 8192
	s_nop 0
	global_load_lds_dwordx4 v158, s[86:87]
	s_waitcnt lgkmcnt(6)
	v_mfma_f32_16x16x32_bf16 v[24:27], v[96:99], v[188:191], v[24:27]
	v_mfma_f32_16x16x32_bf16 v[56:59], v[164:167], v[188:191], v[56:59]
	v_mfma_f32_16x16x32_bf16 v[240:243], v[168:171], v[188:191], v[240:243]
	v_mfma_f32_16x16x32_bf16 v[120:123], v[172:175], v[188:191], v[120:123]
	ds_read_b128 v[188:191], v212 offset:43008
	s_add_u32 m0, s1, 12288
	s_nop 0
	global_load_lds_dwordx4 v159, s[86:87]
	s_add_u32 s86, s86, 128
	s_addc_u32 s87, s87, 0
	s_waitcnt lgkmcnt(6)
	v_mfma_f32_16x16x32_bf16 v[28:31], v[96:99], v[192:195], v[28:31]
	v_mfma_f32_16x16x32_bf16 v[60:63], v[164:167], v[192:195], v[60:63]
	v_mfma_f32_16x16x32_bf16 v[248:251], v[168:171], v[192:195], v[248:251]
	v_mfma_f32_16x16x32_bf16 v[124:127], v[172:175], v[192:195], v[124:127]
	s_waitcnt vmcnt(8)
	ds_read_b128 v[192:195], v212 offset:45056
	global_load_dwordx4 v[96:99], v142, s[84:85] offset:0
	s_waitcnt lgkmcnt(6)
	v_mfma_f32_16x16x32_bf16 v[0:3], v[64:67], v[196:199], v[0:3]
	v_mfma_f32_16x16x32_bf16 v[32:35], v[68:71], v[196:199], v[32:35]
	v_mfma_f32_16x16x32_bf16 v[144:147], v[72:75], v[196:199], v[144:147]
	v_mfma_f32_16x16x32_bf16 v[252:255], v[76:79], v[196:199], v[252:255]
	ds_read_b128 v[196:199], v212 offset:47104
	global_load_dwordx4 v[164:167], v150, s[84:85] offset:0
	s_waitcnt lgkmcnt(6)
	v_mfma_f32_16x16x32_bf16 v[4:7], v[64:67], v[200:203], v[4:7]
	v_mfma_f32_16x16x32_bf16 v[36:39], v[68:71], v[200:203], v[36:39]
	v_mfma_f32_16x16x32_bf16 v[184:187], v[72:75], v[200:203], v[184:187]
	v_mfma_f32_16x16x32_bf16 v[100:103], v[76:79], v[200:203], v[100:103]
	ds_read_b128 v[200:203], v213 offset:32768
	global_load_dwordx4 v[168:171], v142, s[92:93] offset:0
	s_waitcnt lgkmcnt(6)
	v_mfma_f32_16x16x32_bf16 v[8:11], v[64:67], v[160:163], v[8:11]
	v_mfma_f32_16x16x32_bf16 v[40:43], v[68:71], v[160:163], v[40:43]
	v_mfma_f32_16x16x32_bf16 v[204:207], v[72:75], v[160:163], v[204:207]
	v_mfma_f32_16x16x32_bf16 v[104:107], v[76:79], v[160:163], v[104:107]
	ds_read_b128 v[160:163], v213 offset:34816
	global_load_dwordx4 v[172:175], v150, s[92:93] offset:0
	s_waitcnt lgkmcnt(6)
	v_mfma_f32_16x16x32_bf16 v[12:15], v[64:67], v[176:179], v[12:15]
	v_mfma_f32_16x16x32_bf16 v[44:47], v[68:71], v[176:179], v[44:47]
	v_mfma_f32_16x16x32_bf16 v[208:211], v[72:75], v[176:179], v[208:211]
	v_mfma_f32_16x16x32_bf16 v[108:111], v[76:79], v[176:179], v[108:111]
	ds_read_b128 v[176:179], v213 offset:36864
	s_waitcnt lgkmcnt(6)
	v_mfma_f32_16x16x32_bf16 v[16:19], v[64:67], v[180:183], v[16:19]
	v_mfma_f32_16x16x32_bf16 v[48:51], v[68:71], v[180:183], v[48:51]
	v_mfma_f32_16x16x32_bf16 v[232:235], v[72:75], v[180:183], v[232:235]
	v_mfma_f32_16x16x32_bf16 v[112:115], v[76:79], v[180:183], v[112:115]
	ds_read_b128 v[180:183], v213 offset:38912
	s_waitcnt lgkmcnt(6)
	v_mfma_f32_16x16x32_bf16 v[20:23], v[64:67], v[188:191], v[20:23]
	v_mfma_f32_16x16x32_bf16 v[52:55], v[68:71], v[188:191], v[52:55]
	v_mfma_f32_16x16x32_bf16 v[236:239], v[72:75], v[188:191], v[236:239]
	v_mfma_f32_16x16x32_bf16 v[116:119], v[76:79], v[188:191], v[116:119]
	ds_read_b128 v[188:191], v213 offset:40960
	s_waitcnt lgkmcnt(6)
	v_mfma_f32_16x16x32_bf16 v[24:27], v[64:67], v[192:195], v[24:27]
	v_mfma_f32_16x16x32_bf16 v[56:59], v[68:71], v[192:195], v[56:59]
	v_mfma_f32_16x16x32_bf16 v[240:243], v[72:75], v[192:195], v[240:243]
	v_mfma_f32_16x16x32_bf16 v[120:123], v[76:79], v[192:195], v[120:123]
	ds_read_b128 v[192:195], v213 offset:43008
	s_waitcnt lgkmcnt(6)
	v_mfma_f32_16x16x32_bf16 v[28:31], v[64:67], v[196:199], v[28:31]
	v_mfma_f32_16x16x32_bf16 v[60:63], v[68:71], v[196:199], v[60:63]
	v_mfma_f32_16x16x32_bf16 v[248:251], v[72:75], v[196:199], v[248:251]
	v_mfma_f32_16x16x32_bf16 v[124:127], v[76:79], v[196:199], v[124:127]
	s_waitcnt vmcnt(16)
	s_barrier
	s_waitcnt vmcnt(8)
	ds_read_b128 v[196:199], v213 offset:45056
	global_load_dwordx4 v[64:67], v142, s[84:85] offset:1024
	s_waitcnt lgkmcnt(6)
	v_mfma_f32_16x16x32_bf16 v[0:3], v[80:83], v[200:203], v[0:3]
	v_mfma_f32_16x16x32_bf16 v[32:35], v[84:87], v[200:203], v[32:35]
	v_mfma_f32_16x16x32_bf16 v[144:147], v[88:91], v[200:203], v[144:147]
	v_mfma_f32_16x16x32_bf16 v[252:255], v[92:95], v[200:203], v[252:255]
	ds_read_b128 v[200:203], v213 offset:47104
	global_load_dwordx4 v[68:71], v150, s[84:85] offset:1024
	s_waitcnt lgkmcnt(6)
	v_mfma_f32_16x16x32_bf16 v[4:7], v[80:83], v[160:163], v[4:7]
	v_mfma_f32_16x16x32_bf16 v[36:39], v[84:87], v[160:163], v[36:39]
	v_mfma_f32_16x16x32_bf16 v[184:187], v[88:91], v[160:163], v[184:187]
	v_mfma_f32_16x16x32_bf16 v[100:103], v[92:95], v[160:163], v[100:103]
	ds_read_b128 v[160:163], v212 offset:49152
	global_load_dwordx4 v[72:75], v142, s[92:93] offset:1024
	s_waitcnt lgkmcnt(6)
	v_mfma_f32_16x16x32_bf16 v[8:11], v[80:83], v[176:179], v[8:11]
	v_mfma_f32_16x16x32_bf16 v[40:43], v[84:87], v[176:179], v[40:43]
	v_mfma_f32_16x16x32_bf16 v[204:207], v[88:91], v[176:179], v[204:207]
	v_mfma_f32_16x16x32_bf16 v[104:107], v[92:95], v[176:179], v[104:107]
	ds_read_b128 v[176:179], v212 offset:51200
	global_load_dwordx4 v[76:79], v150, s[92:93] offset:1024
	s_add_u32 s84, s84, 0x800
	s_addc_u32 s85, s85, 0
	s_add_u32 s92, s92, 0x800
	s_addc_u32 s93, s93, 0
	s_waitcnt lgkmcnt(6)
	v_mfma_f32_16x16x32_bf16 v[12:15], v[80:83], v[180:183], v[12:15]
	v_mfma_f32_16x16x32_bf16 v[44:47], v[84:87], v[180:183], v[44:47]
	v_mfma_f32_16x16x32_bf16 v[208:211], v[88:91], v[180:183], v[208:211]
	v_mfma_f32_16x16x32_bf16 v[108:111], v[92:95], v[180:183], v[108:111]
	ds_read_b128 v[180:183], v212 offset:53248
	s_add_u32 m0, s1, 16384
	s_nop 0
	global_load_lds_dwordx4 v151, s[86:87]
	s_waitcnt lgkmcnt(6)
	v_mfma_f32_16x16x32_bf16 v[16:19], v[80:83], v[188:191], v[16:19]
	v_mfma_f32_16x16x32_bf16 v[48:51], v[84:87], v[188:191], v[48:51]
	v_mfma_f32_16x16x32_bf16 v[232:235], v[88:91], v[188:191], v[232:235]
	v_mfma_f32_16x16x32_bf16 v[112:115], v[92:95], v[188:191], v[112:115]
	ds_read_b128 v[188:191], v212 offset:55296
	s_add_u32 m0, s1, 20480
	s_nop 0
	global_load_lds_dwordx4 v156, s[86:87]
	s_waitcnt lgkmcnt(6)
	v_mfma_f32_16x16x32_bf16 v[20:23], v[80:83], v[192:195], v[20:23]
	v_mfma_f32_16x16x32_bf16 v[52:55], v[84:87], v[192:195], v[52:55]
	v_mfma_f32_16x16x32_bf16 v[236:239], v[88:91], v[192:195], v[236:239]
	v_mfma_f32_16x16x32_bf16 v[116:119], v[92:95], v[192:195], v[116:119]
	ds_read_b128 v[192:195], v212 offset:57344
	s_add_u32 m0, s1, 24576
	s_nop 0
	global_load_lds_dwordx4 v158, s[86:87]
	s_waitcnt lgkmcnt(6)
	v_mfma_f32_16x16x32_bf16 v[24:27], v[80:83], v[196:199], v[24:27]
	v_mfma_f32_16x16x32_bf16 v[56:59], v[84:87], v[196:199], v[56:59]
	v_mfma_f32_16x16x32_bf16 v[240:243], v[88:91], v[196:199], v[240:243]
	v_mfma_f32_16x16x32_bf16 v[120:123], v[92:95], v[196:199], v[120:123]
	ds_read_b128 v[196:199], v212 offset:59392
	s_add_u32 m0, s1, 28672
	s_nop 0
	global_load_lds_dwordx4 v159, s[86:87]
	s_add_u32 s86, s86, 128
	s_addc_u32 s87, s87, 0
	s_waitcnt lgkmcnt(6)
	v_mfma_f32_16x16x32_bf16 v[28:31], v[80:83], v[200:203], v[28:31]
	v_mfma_f32_16x16x32_bf16 v[60:63], v[84:87], v[200:203], v[60:63]
	v_mfma_f32_16x16x32_bf16 v[248:251], v[88:91], v[200:203], v[248:251]
	v_mfma_f32_16x16x32_bf16 v[124:127], v[92:95], v[200:203], v[124:127]
	s_waitcnt vmcnt(8)
	ds_read_b128 v[200:203], v212 offset:61440
	global_load_dwordx4 v[80:83], v142, s[84:85] offset:0
	s_waitcnt lgkmcnt(6)
	v_mfma_f32_16x16x32_bf16 v[0:3], v[96:99], v[160:163], v[0:3]
	v_mfma_f32_16x16x32_bf16 v[32:35], v[164:167], v[160:163], v[32:35]
	v_mfma_f32_16x16x32_bf16 v[144:147], v[168:171], v[160:163], v[144:147]
	v_mfma_f32_16x16x32_bf16 v[252:255], v[172:175], v[160:163], v[252:255]
	ds_read_b128 v[160:163], v212 offset:63488
	global_load_dwordx4 v[84:87], v150, s[84:85] offset:0
	s_waitcnt lgkmcnt(6)
	v_mfma_f32_16x16x32_bf16 v[4:7], v[96:99], v[176:179], v[4:7]
	v_mfma_f32_16x16x32_bf16 v[36:39], v[164:167], v[176:179], v[36:39]
	v_mfma_f32_16x16x32_bf16 v[184:187], v[168:171], v[176:179], v[184:187]
	v_mfma_f32_16x16x32_bf16 v[100:103], v[172:175], v[176:179], v[100:103]
	ds_read_b128 v[176:179], v213 offset:49152
	global_load_dwordx4 v[88:91], v142, s[92:93] offset:0
	s_waitcnt lgkmcnt(6)
	v_mfma_f32_16x16x32_bf16 v[8:11], v[96:99], v[180:183], v[8:11]
	v_mfma_f32_16x16x32_bf16 v[40:43], v[164:167], v[180:183], v[40:43]
	v_mfma_f32_16x16x32_bf16 v[204:207], v[168:171], v[180:183], v[204:207]
	v_mfma_f32_16x16x32_bf16 v[104:107], v[172:175], v[180:183], v[104:107]
	ds_read_b128 v[180:183], v213 offset:51200
	global_load_dwordx4 v[92:95], v150, s[92:93] offset:0
	s_waitcnt lgkmcnt(6)
	v_mfma_f32_16x16x32_bf16 v[12:15], v[96:99], v[188:191], v[12:15]
	v_mfma_f32_16x16x32_bf16 v[44:47], v[164:167], v[188:191], v[44:47]
	v_mfma_f32_16x16x32_bf16 v[208:211], v[168:171], v[188:191], v[208:211]
	v_mfma_f32_16x16x32_bf16 v[108:111], v[172:175], v[188:191], v[108:111]
	ds_read_b128 v[188:191], v213 offset:53248
	s_waitcnt lgkmcnt(6)
	v_mfma_f32_16x16x32_bf16 v[16:19], v[96:99], v[192:195], v[16:19]
	v_mfma_f32_16x16x32_bf16 v[48:51], v[164:167], v[192:195], v[48:51]
	v_mfma_f32_16x16x32_bf16 v[232:235], v[168:171], v[192:195], v[232:235]
	v_mfma_f32_16x16x32_bf16 v[112:115], v[172:175], v[192:195], v[112:115]
	ds_read_b128 v[192:195], v213 offset:55296
	s_waitcnt lgkmcnt(6)
	v_mfma_f32_16x16x32_bf16 v[20:23], v[96:99], v[196:199], v[20:23]
	v_mfma_f32_16x16x32_bf16 v[52:55], v[164:167], v[196:199], v[52:55]
	v_mfma_f32_16x16x32_bf16 v[236:239], v[168:171], v[196:199], v[236:239]
	v_mfma_f32_16x16x32_bf16 v[116:119], v[172:175], v[196:199], v[116:119]
	ds_read_b128 v[196:199], v213 offset:57344
	s_waitcnt lgkmcnt(6)
	v_mfma_f32_16x16x32_bf16 v[24:27], v[96:99], v[200:203], v[24:27]
	v_mfma_f32_16x16x32_bf16 v[56:59], v[164:167], v[200:203], v[56:59]
	v_mfma_f32_16x16x32_bf16 v[240:243], v[168:171], v[200:203], v[240:243]
	v_mfma_f32_16x16x32_bf16 v[120:123], v[172:175], v[200:203], v[120:123]
	ds_read_b128 v[200:203], v213 offset:59392
	s_waitcnt lgkmcnt(6)
	v_mfma_f32_16x16x32_bf16 v[28:31], v[96:99], v[160:163], v[28:31]
	v_mfma_f32_16x16x32_bf16 v[60:63], v[164:167], v[160:163], v[60:63]
	v_mfma_f32_16x16x32_bf16 v[248:251], v[168:171], v[160:163], v[248:251]
	v_mfma_f32_16x16x32_bf16 v[124:127], v[172:175], v[160:163], v[124:127]
	s_waitcnt vmcnt(16)
	s_barrier
	s_waitcnt vmcnt(8)
	ds_read_b128 v[160:163], v213 offset:61440
	global_load_dwordx4 v[96:99], v142, s[84:85] offset:1024
	s_waitcnt lgkmcnt(6)
	v_mfma_f32_16x16x32_bf16 v[0:3], v[64:67], v[176:179], v[0:3]
	v_mfma_f32_16x16x32_bf16 v[32:35], v[68:71], v[176:179], v[32:35]
	v_mfma_f32_16x16x32_bf16 v[144:147], v[72:75], v[176:179], v[144:147]
	v_mfma_f32_16x16x32_bf16 v[252:255], v[76:79], v[176:179], v[252:255]
	ds_read_b128 v[176:179], v213 offset:63488
	global_load_dwordx4 v[164:167], v150, s[84:85] offset:1024
	s_waitcnt lgkmcnt(6)
	v_mfma_f32_16x16x32_bf16 v[4:7], v[64:67], v[180:183], v[4:7]
	v_mfma_f32_16x16x32_bf16 v[36:39], v[68:71], v[180:183], v[36:39]
	v_mfma_f32_16x16x32_bf16 v[184:187], v[72:75], v[180:183], v[184:187]
	v_mfma_f32_16x16x32_bf16 v[100:103], v[76:79], v[180:183], v[100:103]
	ds_read_b128 v[180:183], v212 offset:0
	global_load_dwordx4 v[168:171], v142, s[92:93] offset:1024
	s_waitcnt lgkmcnt(6)
	v_mfma_f32_16x16x32_bf16 v[8:11], v[64:67], v[188:191], v[8:11]
	v_mfma_f32_16x16x32_bf16 v[40:43], v[68:71], v[188:191], v[40:43]
	v_mfma_f32_16x16x32_bf16 v[204:207], v[72:75], v[188:191], v[204:207]
	v_mfma_f32_16x16x32_bf16 v[104:107], v[76:79], v[188:191], v[104:107]
	ds_read_b128 v[188:191], v212 offset:2048
	global_load_dwordx4 v[172:175], v150, s[92:93] offset:1024
	s_add_u32 s84, s84, 0x800
	s_addc_u32 s85, s85, 0
	s_add_u32 s92, s92, 0x800
	s_addc_u32 s93, s93, 0
	s_waitcnt lgkmcnt(6)
	v_mfma_f32_16x16x32_bf16 v[12:15], v[64:67], v[192:195], v[12:15]
	v_mfma_f32_16x16x32_bf16 v[44:47], v[68:71], v[192:195], v[44:47]
	v_mfma_f32_16x16x32_bf16 v[208:211], v[72:75], v[192:195], v[208:211]
	v_mfma_f32_16x16x32_bf16 v[108:111], v[76:79], v[192:195], v[108:111]
	ds_read_b128 v[192:195], v212 offset:4096
	s_add_u32 m0, s1, 32768
	s_nop 0
	global_load_lds_dwordx4 v151, s[86:87]
	s_waitcnt lgkmcnt(6)
	v_mfma_f32_16x16x32_bf16 v[16:19], v[64:67], v[196:199], v[16:19]
	v_mfma_f32_16x16x32_bf16 v[48:51], v[68:71], v[196:199], v[48:51]
	v_mfma_f32_16x16x32_bf16 v[232:235], v[72:75], v[196:199], v[232:235]
	v_mfma_f32_16x16x32_bf16 v[112:115], v[76:79], v[196:199], v[112:115]
	ds_read_b128 v[196:199], v212 offset:6144
	s_add_u32 m0, s1, 36864
	s_nop 0
	global_load_lds_dwordx4 v156, s[86:87]
	s_waitcnt lgkmcnt(6)
	v_mfma_f32_16x16x32_bf16 v[20:23], v[64:67], v[200:203], v[20:23]
	v_mfma_f32_16x16x32_bf16 v[52:55], v[68:71], v[200:203], v[52:55]
	v_mfma_f32_16x16x32_bf16 v[236:239], v[72:75], v[200:203], v[236:239]
	v_mfma_f32_16x16x32_bf16 v[116:119], v[76:79], v[200:203], v[116:119]
	ds_read_b128 v[200:203], v212 offset:8192
	s_add_u32 m0, s1, 40960
	s_nop 0
	global_load_lds_dwordx4 v158, s[86:87]
	s_waitcnt lgkmcnt(6)
	v_mfma_f32_16x16x32_bf16 v[24:27], v[64:67], v[160:163], v[24:27]
	v_mfma_f32_16x16x32_bf16 v[56:59], v[68:71], v[160:163], v[56:59]
	v_mfma_f32_16x16x32_bf16 v[240:243], v[72:75], v[160:163], v[240:243]
	v_mfma_f32_16x16x32_bf16 v[120:123], v[76:79], v[160:163], v[120:123]
	ds_read_b128 v[160:163], v212 offset:10240
	s_add_u32 m0, s1, 45056
	s_nop 0
	global_load_lds_dwordx4 v159, s[86:87]
	s_add_u32 s86, s86, 128
	s_addc_u32 s87, s87, 0
	s_waitcnt lgkmcnt(6)
	v_mfma_f32_16x16x32_bf16 v[28:31], v[64:67], v[176:179], v[28:31]
	v_mfma_f32_16x16x32_bf16 v[60:63], v[68:71], v[176:179], v[60:63]
	v_mfma_f32_16x16x32_bf16 v[248:251], v[72:75], v[176:179], v[248:251]
	v_mfma_f32_16x16x32_bf16 v[124:127], v[76:79], v[176:179], v[124:127]
	s_waitcnt vmcnt(8)
	ds_read_b128 v[176:179], v212 offset:12288
	global_load_dwordx4 v[64:67], v142, s[84:85] offset:0
	s_waitcnt lgkmcnt(6)
	v_mfma_f32_16x16x32_bf16 v[0:3], v[80:83], v[180:183], v[0:3]
	v_mfma_f32_16x16x32_bf16 v[32:35], v[84:87], v[180:183], v[32:35]
	v_mfma_f32_16x16x32_bf16 v[144:147], v[88:91], v[180:183], v[144:147]
	v_mfma_f32_16x16x32_bf16 v[252:255], v[92:95], v[180:183], v[252:255]
	ds_read_b128 v[180:183], v212 offset:14336
	global_load_dwordx4 v[68:71], v150, s[84:85] offset:0
	s_waitcnt lgkmcnt(6)
	v_mfma_f32_16x16x32_bf16 v[4:7], v[80:83], v[188:191], v[4:7]
	v_mfma_f32_16x16x32_bf16 v[36:39], v[84:87], v[188:191], v[36:39]
	v_mfma_f32_16x16x32_bf16 v[184:187], v[88:91], v[188:191], v[184:187]
	v_mfma_f32_16x16x32_bf16 v[100:103], v[92:95], v[188:191], v[100:103]
	ds_read_b128 v[188:191], v213 offset:0
	global_load_dwordx4 v[72:75], v142, s[92:93] offset:0
	s_waitcnt lgkmcnt(6)
	v_mfma_f32_16x16x32_bf16 v[8:11], v[80:83], v[192:195], v[8:11]
	v_mfma_f32_16x16x32_bf16 v[40:43], v[84:87], v[192:195], v[40:43]
	v_mfma_f32_16x16x32_bf16 v[204:207], v[88:91], v[192:195], v[204:207]
	v_mfma_f32_16x16x32_bf16 v[104:107], v[92:95], v[192:195], v[104:107]
	ds_read_b128 v[192:195], v213 offset:2048
	global_load_dwordx4 v[76:79], v150, s[92:93] offset:0
	s_waitcnt lgkmcnt(6)
	v_mfma_f32_16x16x32_bf16 v[12:15], v[80:83], v[196:199], v[12:15]
	v_mfma_f32_16x16x32_bf16 v[44:47], v[84:87], v[196:199], v[44:47]
	v_mfma_f32_16x16x32_bf16 v[208:211], v[88:91], v[196:199], v[208:211]
	v_mfma_f32_16x16x32_bf16 v[108:111], v[92:95], v[196:199], v[108:111]
	ds_read_b128 v[196:199], v213 offset:4096
	s_waitcnt lgkmcnt(6)
	v_mfma_f32_16x16x32_bf16 v[16:19], v[80:83], v[200:203], v[16:19]
	v_mfma_f32_16x16x32_bf16 v[48:51], v[84:87], v[200:203], v[48:51]
	v_mfma_f32_16x16x32_bf16 v[232:235], v[88:91], v[200:203], v[232:235]
	v_mfma_f32_16x16x32_bf16 v[112:115], v[92:95], v[200:203], v[112:115]
	ds_read_b128 v[200:203], v213 offset:6144
	s_waitcnt lgkmcnt(6)
	v_mfma_f32_16x16x32_bf16 v[20:23], v[80:83], v[160:163], v[20:23]
	v_mfma_f32_16x16x32_bf16 v[52:55], v[84:87], v[160:163], v[52:55]
	v_mfma_f32_16x16x32_bf16 v[236:239], v[88:91], v[160:163], v[236:239]
	v_mfma_f32_16x16x32_bf16 v[116:119], v[92:95], v[160:163], v[116:119]
	ds_read_b128 v[160:163], v213 offset:8192
	s_waitcnt lgkmcnt(6)
	v_mfma_f32_16x16x32_bf16 v[24:27], v[80:83], v[176:179], v[24:27]
	v_mfma_f32_16x16x32_bf16 v[56:59], v[84:87], v[176:179], v[56:59]
	v_mfma_f32_16x16x32_bf16 v[240:243], v[88:91], v[176:179], v[240:243]
	v_mfma_f32_16x16x32_bf16 v[120:123], v[92:95], v[176:179], v[120:123]
	ds_read_b128 v[176:179], v213 offset:10240
	s_waitcnt lgkmcnt(6)
	v_mfma_f32_16x16x32_bf16 v[28:31], v[80:83], v[180:183], v[28:31]
	v_mfma_f32_16x16x32_bf16 v[60:63], v[84:87], v[180:183], v[60:63]
	v_mfma_f32_16x16x32_bf16 v[248:251], v[88:91], v[180:183], v[248:251]
	v_mfma_f32_16x16x32_bf16 v[124:127], v[92:95], v[180:183], v[124:127]
	s_waitcnt vmcnt(16)
	s_barrier
	s_waitcnt vmcnt(8)
	ds_read_b128 v[180:183], v213 offset:12288
	global_load_dwordx4 v[80:83], v142, s[84:85] offset:1024
	s_waitcnt lgkmcnt(6)
	v_mfma_f32_16x16x32_bf16 v[0:3], v[96:99], v[188:191], v[0:3]
	v_mfma_f32_16x16x32_bf16 v[32:35], v[164:167], v[188:191], v[32:35]
	v_mfma_f32_16x16x32_bf16 v[144:147], v[168:171], v[188:191], v[144:147]
	v_mfma_f32_16x16x32_bf16 v[252:255], v[172:175], v[188:191], v[252:255]
	ds_read_b128 v[188:191], v213 offset:14336
	global_load_dwordx4 v[84:87], v150, s[84:85] offset:1024
	s_waitcnt lgkmcnt(6)
	v_mfma_f32_16x16x32_bf16 v[4:7], v[96:99], v[192:195], v[4:7]
	v_mfma_f32_16x16x32_bf16 v[36:39], v[164:167], v[192:195], v[36:39]
	v_mfma_f32_16x16x32_bf16 v[184:187], v[168:171], v[192:195], v[184:187]
	v_mfma_f32_16x16x32_bf16 v[100:103], v[172:175], v[192:195], v[100:103]
	ds_read_b128 v[192:195], v212 offset:16384
	global_load_dwordx4 v[88:91], v142, s[92:93] offset:1024
	s_waitcnt lgkmcnt(6)
	v_mfma_f32_16x16x32_bf16 v[8:11], v[96:99], v[196:199], v[8:11]
	v_mfma_f32_16x16x32_bf16 v[40:43], v[164:167], v[196:199], v[40:43]
	v_mfma_f32_16x16x32_bf16 v[204:207], v[168:171], v[196:199], v[204:207]
	v_mfma_f32_16x16x32_bf16 v[104:107], v[172:175], v[196:199], v[104:107]
	ds_read_b128 v[196:199], v212 offset:18432
	global_load_dwordx4 v[92:95], v150, s[92:93] offset:1024
	s_add_u32 s84, s84, 0x800
	s_addc_u32 s85, s85, 0
	s_add_u32 s92, s92, 0x800
	s_addc_u32 s93, s93, 0
	s_waitcnt lgkmcnt(6)
	v_mfma_f32_16x16x32_bf16 v[12:15], v[96:99], v[200:203], v[12:15]
	v_mfma_f32_16x16x32_bf16 v[44:47], v[164:167], v[200:203], v[44:47]
	v_mfma_f32_16x16x32_bf16 v[208:211], v[168:171], v[200:203], v[208:211]
	v_mfma_f32_16x16x32_bf16 v[108:111], v[172:175], v[200:203], v[108:111]
	ds_read_b128 v[200:203], v212 offset:20480
	s_add_u32 m0, s1, 49152
	s_nop 0
	global_load_lds_dwordx4 v151, s[86:87]
	s_waitcnt lgkmcnt(6)
	v_mfma_f32_16x16x32_bf16 v[16:19], v[96:99], v[160:163], v[16:19]
	v_mfma_f32_16x16x32_bf16 v[48:51], v[164:167], v[160:163], v[48:51]
	v_mfma_f32_16x16x32_bf16 v[232:235], v[168:171], v[160:163], v[232:235]
	v_mfma_f32_16x16x32_bf16 v[112:115], v[172:175], v[160:163], v[112:115]
	ds_read_b128 v[160:163], v212 offset:22528
	s_add_u32 m0, s1, 53248
	s_nop 0
	global_load_lds_dwordx4 v156, s[86:87]
	s_waitcnt lgkmcnt(6)
	v_mfma_f32_16x16x32_bf16 v[20:23], v[96:99], v[176:179], v[20:23]
	v_mfma_f32_16x16x32_bf16 v[52:55], v[164:167], v[176:179], v[52:55]
	v_mfma_f32_16x16x32_bf16 v[236:239], v[168:171], v[176:179], v[236:239]
	v_mfma_f32_16x16x32_bf16 v[116:119], v[172:175], v[176:179], v[116:119]
	ds_read_b128 v[176:179], v212 offset:24576
	s_add_u32 m0, s1, 57344
	s_nop 0
	global_load_lds_dwordx4 v158, s[86:87]
	s_waitcnt lgkmcnt(6)
	v_mfma_f32_16x16x32_bf16 v[24:27], v[96:99], v[180:183], v[24:27]
	v_mfma_f32_16x16x32_bf16 v[56:59], v[164:167], v[180:183], v[56:59]
	v_mfma_f32_16x16x32_bf16 v[240:243], v[168:171], v[180:183], v[240:243]
	v_mfma_f32_16x16x32_bf16 v[120:123], v[172:175], v[180:183], v[120:123]
	ds_read_b128 v[180:183], v212 offset:26624
	s_add_u32 m0, s1, 61440
	s_nop 0
	global_load_lds_dwordx4 v159, s[86:87]
	s_add_u32 s86, s86, 128
	s_addc_u32 s87, s87, 0
	s_waitcnt lgkmcnt(6)
	v_mfma_f32_16x16x32_bf16 v[28:31], v[96:99], v[188:191], v[28:31]
	v_mfma_f32_16x16x32_bf16 v[60:63], v[164:167], v[188:191], v[60:63]
	v_mfma_f32_16x16x32_bf16 v[248:251], v[168:171], v[188:191], v[248:251]
	v_mfma_f32_16x16x32_bf16 v[124:127], v[172:175], v[188:191], v[124:127]
	s_waitcnt vmcnt(8)
	ds_read_b128 v[188:191], v212 offset:28672
	global_load_dwordx4 v[96:99], v142, s[84:85] offset:0
	s_waitcnt lgkmcnt(6)
	v_mfma_f32_16x16x32_bf16 v[0:3], v[64:67], v[192:195], v[0:3]
	v_mfma_f32_16x16x32_bf16 v[32:35], v[68:71], v[192:195], v[32:35]
	v_mfma_f32_16x16x32_bf16 v[144:147], v[72:75], v[192:195], v[144:147]
	v_mfma_f32_16x16x32_bf16 v[252:255], v[76:79], v[192:195], v[252:255]
	ds_read_b128 v[192:195], v212 offset:30720
	global_load_dwordx4 v[164:167], v150, s[84:85] offset:0
	s_waitcnt lgkmcnt(6)
	v_mfma_f32_16x16x32_bf16 v[4:7], v[64:67], v[196:199], v[4:7]
	v_mfma_f32_16x16x32_bf16 v[36:39], v[68:71], v[196:199], v[36:39]
	v_mfma_f32_16x16x32_bf16 v[184:187], v[72:75], v[196:199], v[184:187]
	v_mfma_f32_16x16x32_bf16 v[100:103], v[76:79], v[196:199], v[100:103]
	ds_read_b128 v[196:199], v213 offset:16384
	global_load_dwordx4 v[168:171], v142, s[92:93] offset:0
	s_waitcnt lgkmcnt(6)
	v_mfma_f32_16x16x32_bf16 v[8:11], v[64:67], v[200:203], v[8:11]
	v_mfma_f32_16x16x32_bf16 v[40:43], v[68:71], v[200:203], v[40:43]
	v_mfma_f32_16x16x32_bf16 v[204:207], v[72:75], v[200:203], v[204:207]
	v_mfma_f32_16x16x32_bf16 v[104:107], v[76:79], v[200:203], v[104:107]
	ds_read_b128 v[200:203], v213 offset:18432
	global_load_dwordx4 v[172:175], v150, s[92:93] offset:0
	s_waitcnt lgkmcnt(6)
	v_mfma_f32_16x16x32_bf16 v[12:15], v[64:67], v[160:163], v[12:15]
	v_mfma_f32_16x16x32_bf16 v[44:47], v[68:71], v[160:163], v[44:47]
	v_mfma_f32_16x16x32_bf16 v[208:211], v[72:75], v[160:163], v[208:211]
	v_mfma_f32_16x16x32_bf16 v[108:111], v[76:79], v[160:163], v[108:111]
	ds_read_b128 v[160:163], v213 offset:20480
	s_waitcnt lgkmcnt(6)
	v_mfma_f32_16x16x32_bf16 v[16:19], v[64:67], v[176:179], v[16:19]
	v_mfma_f32_16x16x32_bf16 v[48:51], v[68:71], v[176:179], v[48:51]
	v_mfma_f32_16x16x32_bf16 v[232:235], v[72:75], v[176:179], v[232:235]
	v_mfma_f32_16x16x32_bf16 v[112:115], v[76:79], v[176:179], v[112:115]
	ds_read_b128 v[176:179], v213 offset:22528
	s_waitcnt lgkmcnt(6)
	v_mfma_f32_16x16x32_bf16 v[20:23], v[64:67], v[180:183], v[20:23]
	v_mfma_f32_16x16x32_bf16 v[52:55], v[68:71], v[180:183], v[52:55]
	v_mfma_f32_16x16x32_bf16 v[236:239], v[72:75], v[180:183], v[236:239]
	v_mfma_f32_16x16x32_bf16 v[116:119], v[76:79], v[180:183], v[116:119]
	ds_read_b128 v[180:183], v213 offset:24576
	s_waitcnt lgkmcnt(6)
	v_mfma_f32_16x16x32_bf16 v[24:27], v[64:67], v[188:191], v[24:27]
	v_mfma_f32_16x16x32_bf16 v[56:59], v[68:71], v[188:191], v[56:59]
	v_mfma_f32_16x16x32_bf16 v[240:243], v[72:75], v[188:191], v[240:243]
	v_mfma_f32_16x16x32_bf16 v[120:123], v[76:79], v[188:191], v[120:123]
	ds_read_b128 v[188:191], v213 offset:26624
	s_waitcnt lgkmcnt(6)
	v_mfma_f32_16x16x32_bf16 v[28:31], v[64:67], v[192:195], v[28:31]
	v_mfma_f32_16x16x32_bf16 v[60:63], v[68:71], v[192:195], v[60:63]
	v_mfma_f32_16x16x32_bf16 v[248:251], v[72:75], v[192:195], v[248:251]
	v_mfma_f32_16x16x32_bf16 v[124:127], v[76:79], v[192:195], v[124:127]
	s_waitcnt vmcnt(16)
	s_barrier
	s_waitcnt vmcnt(8)
	ds_read_b128 v[192:195], v213 offset:28672
	global_load_dwordx4 v[64:67], v142, s[84:85] offset:1024
	s_waitcnt lgkmcnt(6)
	v_mfma_f32_16x16x32_bf16 v[0:3], v[80:83], v[196:199], v[0:3]
	v_mfma_f32_16x16x32_bf16 v[32:35], v[84:87], v[196:199], v[32:35]
	v_mfma_f32_16x16x32_bf16 v[144:147], v[88:91], v[196:199], v[144:147]
	v_mfma_f32_16x16x32_bf16 v[252:255], v[92:95], v[196:199], v[252:255]
	ds_read_b128 v[196:199], v213 offset:30720
	global_load_dwordx4 v[68:71], v150, s[84:85] offset:1024
	s_waitcnt lgkmcnt(6)
	v_mfma_f32_16x16x32_bf16 v[4:7], v[80:83], v[200:203], v[4:7]
	v_mfma_f32_16x16x32_bf16 v[36:39], v[84:87], v[200:203], v[36:39]
	v_mfma_f32_16x16x32_bf16 v[184:187], v[88:91], v[200:203], v[184:187]
	v_mfma_f32_16x16x32_bf16 v[100:103], v[92:95], v[200:203], v[100:103]
	ds_read_b128 v[200:203], v212 offset:32768
	global_load_dwordx4 v[72:75], v142, s[92:93] offset:1024
	s_waitcnt lgkmcnt(6)
	v_mfma_f32_16x16x32_bf16 v[8:11], v[80:83], v[160:163], v[8:11]
	v_mfma_f32_16x16x32_bf16 v[40:43], v[84:87], v[160:163], v[40:43]
	v_mfma_f32_16x16x32_bf16 v[204:207], v[88:91], v[160:163], v[204:207]
	v_mfma_f32_16x16x32_bf16 v[104:107], v[92:95], v[160:163], v[104:107]
	ds_read_b128 v[160:163], v212 offset:34816
	global_load_dwordx4 v[76:79], v150, s[92:93] offset:1024
	s_add_u32 s84, s84, 0x800
	s_addc_u32 s85, s85, 0
	s_add_u32 s92, s92, 0x800
	s_addc_u32 s93, s93, 0
	s_waitcnt lgkmcnt(6)
	v_mfma_f32_16x16x32_bf16 v[12:15], v[80:83], v[176:179], v[12:15]
	v_mfma_f32_16x16x32_bf16 v[44:47], v[84:87], v[176:179], v[44:47]
	v_mfma_f32_16x16x32_bf16 v[208:211], v[88:91], v[176:179], v[208:211]
	v_mfma_f32_16x16x32_bf16 v[108:111], v[92:95], v[176:179], v[108:111]
	ds_read_b128 v[176:179], v212 offset:36864
	s_add_u32 m0, s1, 0
	s_nop 0
	global_load_lds_dwordx4 v151, s[86:87]
	s_waitcnt lgkmcnt(6)
	v_mfma_f32_16x16x32_bf16 v[16:19], v[80:83], v[180:183], v[16:19]
	v_mfma_f32_16x16x32_bf16 v[48:51], v[84:87], v[180:183], v[48:51]
	v_mfma_f32_16x16x32_bf16 v[232:235], v[88:91], v[180:183], v[232:235]
	v_mfma_f32_16x16x32_bf16 v[112:115], v[92:95], v[180:183], v[112:115]
	ds_read_b128 v[180:183], v212 offset:38912
	s_add_u32 m0, s1, 4096
	s_nop 0
	global_load_lds_dwordx4 v156, s[86:87]
	s_waitcnt lgkmcnt(6)
	v_mfma_f32_16x16x32_bf16 v[20:23], v[80:83], v[188:191], v[20:23]
	v_mfma_f32_16x16x32_bf16 v[52:55], v[84:87], v[188:191], v[52:55]
	v_mfma_f32_16x16x32_bf16 v[236:239], v[88:91], v[188:191], v[236:239]
	v_mfma_f32_16x16x32_bf16 v[116:119], v[92:95], v[188:191], v[116:119]
	ds_read_b128 v[188:191], v212 offset:40960
	s_add_u32 m0, s1, 8192
	s_nop 0
	global_load_lds_dwordx4 v158, s[86:87]
	s_waitcnt lgkmcnt(6)
	v_mfma_f32_16x16x32_bf16 v[24:27], v[80:83], v[192:195], v[24:27]
	v_mfma_f32_16x16x32_bf16 v[56:59], v[84:87], v[192:195], v[56:59]
	v_mfma_f32_16x16x32_bf16 v[240:243], v[88:91], v[192:195], v[240:243]
	v_mfma_f32_16x16x32_bf16 v[120:123], v[92:95], v[192:195], v[120:123]
	ds_read_b128 v[192:195], v212 offset:43008
	s_add_u32 m0, s1, 12288
	s_nop 0
	global_load_lds_dwordx4 v159, s[86:87]
	s_add_u32 s86, s86, 128
	s_addc_u32 s87, s87, 0
	s_waitcnt lgkmcnt(6)
	v_mfma_f32_16x16x32_bf16 v[28:31], v[80:83], v[196:199], v[28:31]
	v_mfma_f32_16x16x32_bf16 v[60:63], v[84:87], v[196:199], v[60:63]
	v_mfma_f32_16x16x32_bf16 v[248:251], v[88:91], v[196:199], v[248:251]
	v_mfma_f32_16x16x32_bf16 v[124:127], v[92:95], v[196:199], v[124:127]
	s_waitcnt vmcnt(8)
	ds_read_b128 v[196:199], v212 offset:45056
	global_load_dwordx4 v[80:83], v142, s[84:85] offset:0
	s_waitcnt lgkmcnt(6)
	v_mfma_f32_16x16x32_bf16 v[0:3], v[96:99], v[200:203], v[0:3]
	v_mfma_f32_16x16x32_bf16 v[32:35], v[164:167], v[200:203], v[32:35]
	v_mfma_f32_16x16x32_bf16 v[144:147], v[168:171], v[200:203], v[144:147]
	v_mfma_f32_16x16x32_bf16 v[252:255], v[172:175], v[200:203], v[252:255]
	ds_read_b128 v[200:203], v212 offset:47104
	global_load_dwordx4 v[84:87], v150, s[84:85] offset:0
	s_waitcnt lgkmcnt(6)
	v_mfma_f32_16x16x32_bf16 v[4:7], v[96:99], v[160:163], v[4:7]
	v_mfma_f32_16x16x32_bf16 v[36:39], v[164:167], v[160:163], v[36:39]
	v_mfma_f32_16x16x32_bf16 v[184:187], v[168:171], v[160:163], v[184:187]
	v_mfma_f32_16x16x32_bf16 v[100:103], v[172:175], v[160:163], v[100:103]
	ds_read_b128 v[160:163], v213 offset:32768
	global_load_dwordx4 v[88:91], v142, s[92:93] offset:0
	s_waitcnt lgkmcnt(6)
	v_mfma_f32_16x16x32_bf16 v[8:11], v[96:99], v[176:179], v[8:11]
	v_mfma_f32_16x16x32_bf16 v[40:43], v[164:167], v[176:179], v[40:43]
	v_mfma_f32_16x16x32_bf16 v[204:207], v[168:171], v[176:179], v[204:207]
	v_mfma_f32_16x16x32_bf16 v[104:107], v[172:175], v[176:179], v[104:107]
	ds_read_b128 v[176:179], v213 offset:34816
	global_load_dwordx4 v[92:95], v150, s[92:93] offset:0
	s_waitcnt lgkmcnt(6)
	v_mfma_f32_16x16x32_bf16 v[12:15], v[96:99], v[180:183], v[12:15]
	v_mfma_f32_16x16x32_bf16 v[44:47], v[164:167], v[180:183], v[44:47]
	v_mfma_f32_16x16x32_bf16 v[208:211], v[168:171], v[180:183], v[208:211]
	v_mfma_f32_16x16x32_bf16 v[108:111], v[172:175], v[180:183], v[108:111]
	ds_read_b128 v[180:183], v213 offset:36864
	s_waitcnt lgkmcnt(6)
	v_mfma_f32_16x16x32_bf16 v[16:19], v[96:99], v[188:191], v[16:19]
	v_mfma_f32_16x16x32_bf16 v[48:51], v[164:167], v[188:191], v[48:51]
	v_mfma_f32_16x16x32_bf16 v[232:235], v[168:171], v[188:191], v[232:235]
	v_mfma_f32_16x16x32_bf16 v[112:115], v[172:175], v[188:191], v[112:115]
	ds_read_b128 v[188:191], v213 offset:38912
	s_waitcnt lgkmcnt(6)
	v_mfma_f32_16x16x32_bf16 v[20:23], v[96:99], v[192:195], v[20:23]
	v_mfma_f32_16x16x32_bf16 v[52:55], v[164:167], v[192:195], v[52:55]
	v_mfma_f32_16x16x32_bf16 v[236:239], v[168:171], v[192:195], v[236:239]
	v_mfma_f32_16x16x32_bf16 v[116:119], v[172:175], v[192:195], v[116:119]
	ds_read_b128 v[192:195], v213 offset:40960
	s_waitcnt lgkmcnt(6)
	v_mfma_f32_16x16x32_bf16 v[24:27], v[96:99], v[196:199], v[24:27]
	v_mfma_f32_16x16x32_bf16 v[56:59], v[164:167], v[196:199], v[56:59]
	v_mfma_f32_16x16x32_bf16 v[240:243], v[168:171], v[196:199], v[240:243]
	v_mfma_f32_16x16x32_bf16 v[120:123], v[172:175], v[196:199], v[120:123]
	ds_read_b128 v[196:199], v213 offset:43008
	s_waitcnt lgkmcnt(6)
	v_mfma_f32_16x16x32_bf16 v[28:31], v[96:99], v[200:203], v[28:31]
	v_mfma_f32_16x16x32_bf16 v[60:63], v[164:167], v[200:203], v[60:63]
	v_mfma_f32_16x16x32_bf16 v[248:251], v[168:171], v[200:203], v[248:251]
	v_mfma_f32_16x16x32_bf16 v[124:127], v[172:175], v[200:203], v[124:127]
	s_waitcnt vmcnt(16)
	s_barrier
	s_waitcnt vmcnt(8)
	ds_read_b128 v[200:203], v213 offset:45056
	global_load_dwordx4 v[96:99], v142, s[84:85] offset:1024
	s_waitcnt lgkmcnt(6)
	v_mfma_f32_16x16x32_bf16 v[0:3], v[64:67], v[160:163], v[0:3]
	v_mfma_f32_16x16x32_bf16 v[32:35], v[68:71], v[160:163], v[32:35]
	v_mfma_f32_16x16x32_bf16 v[144:147], v[72:75], v[160:163], v[144:147]
	v_mfma_f32_16x16x32_bf16 v[252:255], v[76:79], v[160:163], v[252:255]
	ds_read_b128 v[160:163], v213 offset:47104
	global_load_dwordx4 v[164:167], v150, s[84:85] offset:1024
	s_waitcnt lgkmcnt(6)
	v_mfma_f32_16x16x32_bf16 v[4:7], v[64:67], v[176:179], v[4:7]
	v_mfma_f32_16x16x32_bf16 v[36:39], v[68:71], v[176:179], v[36:39]
	v_mfma_f32_16x16x32_bf16 v[184:187], v[72:75], v[176:179], v[184:187]
	v_mfma_f32_16x16x32_bf16 v[100:103], v[76:79], v[176:179], v[100:103]
	ds_read_b128 v[176:179], v212 offset:49152
	global_load_dwordx4 v[168:171], v142, s[92:93] offset:1024
	s_waitcnt lgkmcnt(6)
	v_mfma_f32_16x16x32_bf16 v[8:11], v[64:67], v[180:183], v[8:11]
	v_mfma_f32_16x16x32_bf16 v[40:43], v[68:71], v[180:183], v[40:43]
	v_mfma_f32_16x16x32_bf16 v[204:207], v[72:75], v[180:183], v[204:207]
	v_mfma_f32_16x16x32_bf16 v[104:107], v[76:79], v[180:183], v[104:107]
	ds_read_b128 v[180:183], v212 offset:51200
	global_load_dwordx4 v[172:175], v150, s[92:93] offset:1024
	s_add_u32 s84, s84, 0x800
	s_addc_u32 s85, s85, 0
	s_add_u32 s92, s92, 0x800
	s_addc_u32 s93, s93, 0
	s_waitcnt lgkmcnt(6)
	v_mfma_f32_16x16x32_bf16 v[12:15], v[64:67], v[188:191], v[12:15]
	v_mfma_f32_16x16x32_bf16 v[44:47], v[68:71], v[188:191], v[44:47]
	v_mfma_f32_16x16x32_bf16 v[208:211], v[72:75], v[188:191], v[208:211]
	v_mfma_f32_16x16x32_bf16 v[108:111], v[76:79], v[188:191], v[108:111]
	ds_read_b128 v[188:191], v212 offset:53248
	s_add_u32 m0, s1, 16384
	s_nop 0
	global_load_lds_dwordx4 v151, s[86:87]
	s_waitcnt lgkmcnt(6)
	v_mfma_f32_16x16x32_bf16 v[16:19], v[64:67], v[192:195], v[16:19]
	v_mfma_f32_16x16x32_bf16 v[48:51], v[68:71], v[192:195], v[48:51]
	v_mfma_f32_16x16x32_bf16 v[232:235], v[72:75], v[192:195], v[232:235]
	v_mfma_f32_16x16x32_bf16 v[112:115], v[76:79], v[192:195], v[112:115]
	ds_read_b128 v[192:195], v212 offset:55296
	s_add_u32 m0, s1, 20480
	s_nop 0
	global_load_lds_dwordx4 v156, s[86:87]
	s_waitcnt lgkmcnt(6)
	v_mfma_f32_16x16x32_bf16 v[20:23], v[64:67], v[196:199], v[20:23]
	v_mfma_f32_16x16x32_bf16 v[52:55], v[68:71], v[196:199], v[52:55]
	v_mfma_f32_16x16x32_bf16 v[236:239], v[72:75], v[196:199], v[236:239]
	v_mfma_f32_16x16x32_bf16 v[116:119], v[76:79], v[196:199], v[116:119]
	ds_read_b128 v[196:199], v212 offset:57344
	s_add_u32 m0, s1, 24576
	s_nop 0
	global_load_lds_dwordx4 v158, s[86:87]
	s_waitcnt lgkmcnt(6)
	v_mfma_f32_16x16x32_bf16 v[24:27], v[64:67], v[200:203], v[24:27]
	v_mfma_f32_16x16x32_bf16 v[56:59], v[68:71], v[200:203], v[56:59]
	v_mfma_f32_16x16x32_bf16 v[240:243], v[72:75], v[200:203], v[240:243]
	v_mfma_f32_16x16x32_bf16 v[120:123], v[76:79], v[200:203], v[120:123]
	ds_read_b128 v[200:203], v212 offset:59392
	s_add_u32 m0, s1, 28672
	s_nop 0
	global_load_lds_dwordx4 v159, s[86:87]
	s_add_u32 s86, s86, 128
	s_addc_u32 s87, s87, 0
	s_waitcnt lgkmcnt(6)
	v_mfma_f32_16x16x32_bf16 v[28:31], v[64:67], v[160:163], v[28:31]
	v_mfma_f32_16x16x32_bf16 v[60:63], v[68:71], v[160:163], v[60:63]
	v_mfma_f32_16x16x32_bf16 v[248:251], v[72:75], v[160:163], v[248:251]
	v_mfma_f32_16x16x32_bf16 v[124:127], v[76:79], v[160:163], v[124:127]
	s_waitcnt vmcnt(8)
	ds_read_b128 v[160:163], v212 offset:61440
	global_load_dwordx4 v[64:67], v142, s[84:85] offset:0
	s_waitcnt lgkmcnt(6)
	v_mfma_f32_16x16x32_bf16 v[0:3], v[80:83], v[176:179], v[0:3]
	v_mfma_f32_16x16x32_bf16 v[32:35], v[84:87], v[176:179], v[32:35]
	v_mfma_f32_16x16x32_bf16 v[144:147], v[88:91], v[176:179], v[144:147]
	v_mfma_f32_16x16x32_bf16 v[252:255], v[92:95], v[176:179], v[252:255]
	ds_read_b128 v[176:179], v212 offset:63488
	global_load_dwordx4 v[68:71], v150, s[84:85] offset:0
	s_waitcnt lgkmcnt(6)
	v_mfma_f32_16x16x32_bf16 v[4:7], v[80:83], v[180:183], v[4:7]
	v_mfma_f32_16x16x32_bf16 v[36:39], v[84:87], v[180:183], v[36:39]
	v_mfma_f32_16x16x32_bf16 v[184:187], v[88:91], v[180:183], v[184:187]
	v_mfma_f32_16x16x32_bf16 v[100:103], v[92:95], v[180:183], v[100:103]
	ds_read_b128 v[180:183], v213 offset:49152
	global_load_dwordx4 v[72:75], v142, s[92:93] offset:0
	s_waitcnt lgkmcnt(6)
	v_mfma_f32_16x16x32_bf16 v[8:11], v[80:83], v[188:191], v[8:11]
	v_mfma_f32_16x16x32_bf16 v[40:43], v[84:87], v[188:191], v[40:43]
	v_mfma_f32_16x16x32_bf16 v[204:207], v[88:91], v[188:191], v[204:207]
	v_mfma_f32_16x16x32_bf16 v[104:107], v[92:95], v[188:191], v[104:107]
	ds_read_b128 v[188:191], v213 offset:51200
	global_load_dwordx4 v[76:79], v150, s[92:93] offset:0
	s_waitcnt lgkmcnt(6)
	v_mfma_f32_16x16x32_bf16 v[12:15], v[80:83], v[192:195], v[12:15]
	v_mfma_f32_16x16x32_bf16 v[44:47], v[84:87], v[192:195], v[44:47]
	v_mfma_f32_16x16x32_bf16 v[208:211], v[88:91], v[192:195], v[208:211]
	v_mfma_f32_16x16x32_bf16 v[108:111], v[92:95], v[192:195], v[108:111]
	ds_read_b128 v[192:195], v213 offset:53248
	s_waitcnt lgkmcnt(6)
	v_mfma_f32_16x16x32_bf16 v[16:19], v[80:83], v[196:199], v[16:19]
	v_mfma_f32_16x16x32_bf16 v[48:51], v[84:87], v[196:199], v[48:51]
	v_mfma_f32_16x16x32_bf16 v[232:235], v[88:91], v[196:199], v[232:235]
	v_mfma_f32_16x16x32_bf16 v[112:115], v[92:95], v[196:199], v[112:115]
	ds_read_b128 v[196:199], v213 offset:55296
	s_waitcnt lgkmcnt(6)
	v_mfma_f32_16x16x32_bf16 v[20:23], v[80:83], v[200:203], v[20:23]
	v_mfma_f32_16x16x32_bf16 v[52:55], v[84:87], v[200:203], v[52:55]
	v_mfma_f32_16x16x32_bf16 v[236:239], v[88:91], v[200:203], v[236:239]
	v_mfma_f32_16x16x32_bf16 v[116:119], v[92:95], v[200:203], v[116:119]
	ds_read_b128 v[200:203], v213 offset:57344
	s_waitcnt lgkmcnt(6)
	v_mfma_f32_16x16x32_bf16 v[24:27], v[80:83], v[160:163], v[24:27]
	v_mfma_f32_16x16x32_bf16 v[56:59], v[84:87], v[160:163], v[56:59]
	v_mfma_f32_16x16x32_bf16 v[240:243], v[88:91], v[160:163], v[240:243]
	v_mfma_f32_16x16x32_bf16 v[120:123], v[92:95], v[160:163], v[120:123]
	ds_read_b128 v[160:163], v213 offset:59392
	s_waitcnt lgkmcnt(6)
	v_mfma_f32_16x16x32_bf16 v[28:31], v[80:83], v[176:179], v[28:31]
	v_mfma_f32_16x16x32_bf16 v[60:63], v[84:87], v[176:179], v[60:63]
	v_mfma_f32_16x16x32_bf16 v[248:251], v[88:91], v[176:179], v[248:251]
	v_mfma_f32_16x16x32_bf16 v[124:127], v[92:95], v[176:179], v[124:127]
	s_waitcnt vmcnt(16)
	s_barrier
	s_waitcnt vmcnt(8)
	ds_read_b128 v[176:179], v213 offset:61440
	global_load_dwordx4 v[80:83], v142, s[84:85] offset:1024
	s_waitcnt lgkmcnt(6)
	v_mfma_f32_16x16x32_bf16 v[0:3], v[96:99], v[180:183], v[0:3]
	v_mfma_f32_16x16x32_bf16 v[32:35], v[164:167], v[180:183], v[32:35]
	v_mfma_f32_16x16x32_bf16 v[144:147], v[168:171], v[180:183], v[144:147]
	v_mfma_f32_16x16x32_bf16 v[252:255], v[172:175], v[180:183], v[252:255]
	ds_read_b128 v[180:183], v213 offset:63488
	global_load_dwordx4 v[84:87], v150, s[84:85] offset:1024
	s_waitcnt lgkmcnt(6)
	v_mfma_f32_16x16x32_bf16 v[4:7], v[96:99], v[188:191], v[4:7]
	v_mfma_f32_16x16x32_bf16 v[36:39], v[164:167], v[188:191], v[36:39]
	v_mfma_f32_16x16x32_bf16 v[184:187], v[168:171], v[188:191], v[184:187]
	v_mfma_f32_16x16x32_bf16 v[100:103], v[172:175], v[188:191], v[100:103]
	ds_read_b128 v[188:191], v212 offset:0
	global_load_dwordx4 v[88:91], v142, s[92:93] offset:1024
	s_waitcnt lgkmcnt(6)
	v_mfma_f32_16x16x32_bf16 v[8:11], v[96:99], v[192:195], v[8:11]
	v_mfma_f32_16x16x32_bf16 v[40:43], v[164:167], v[192:195], v[40:43]
	v_mfma_f32_16x16x32_bf16 v[204:207], v[168:171], v[192:195], v[204:207]
	v_mfma_f32_16x16x32_bf16 v[104:107], v[172:175], v[192:195], v[104:107]
	ds_read_b128 v[192:195], v212 offset:2048
	global_load_dwordx4 v[92:95], v150, s[92:93] offset:1024
	s_add_u32 s84, s84, 0x800
	s_addc_u32 s85, s85, 0
	s_add_u32 s92, s92, 0x800
	s_addc_u32 s93, s93, 0
	s_waitcnt lgkmcnt(6)
	v_mfma_f32_16x16x32_bf16 v[12:15], v[96:99], v[196:199], v[12:15]
	v_mfma_f32_16x16x32_bf16 v[44:47], v[164:167], v[196:199], v[44:47]
	v_mfma_f32_16x16x32_bf16 v[208:211], v[168:171], v[196:199], v[208:211]
	v_mfma_f32_16x16x32_bf16 v[108:111], v[172:175], v[196:199], v[108:111]
	ds_read_b128 v[196:199], v212 offset:4096
	s_add_u32 m0, s1, 32768
	s_nop 0
	global_load_lds_dwordx4 v151, s[86:87]
	s_waitcnt lgkmcnt(6)
	v_mfma_f32_16x16x32_bf16 v[16:19], v[96:99], v[200:203], v[16:19]
	v_mfma_f32_16x16x32_bf16 v[48:51], v[164:167], v[200:203], v[48:51]
	v_mfma_f32_16x16x32_bf16 v[232:235], v[168:171], v[200:203], v[232:235]
	v_mfma_f32_16x16x32_bf16 v[112:115], v[172:175], v[200:203], v[112:115]
	ds_read_b128 v[200:203], v212 offset:6144
	s_add_u32 m0, s1, 36864
	s_nop 0
	global_load_lds_dwordx4 v156, s[86:87]
	s_waitcnt lgkmcnt(6)
	v_mfma_f32_16x16x32_bf16 v[20:23], v[96:99], v[160:163], v[20:23]
	v_mfma_f32_16x16x32_bf16 v[52:55], v[164:167], v[160:163], v[52:55]
	v_mfma_f32_16x16x32_bf16 v[236:239], v[168:171], v[160:163], v[236:239]
	v_mfma_f32_16x16x32_bf16 v[116:119], v[172:175], v[160:163], v[116:119]
	ds_read_b128 v[160:163], v212 offset:8192
	s_add_u32 m0, s1, 40960
	s_nop 0
	global_load_lds_dwordx4 v158, s[86:87]
	s_waitcnt lgkmcnt(6)
	v_mfma_f32_16x16x32_bf16 v[24:27], v[96:99], v[176:179], v[24:27]
	v_mfma_f32_16x16x32_bf16 v[56:59], v[164:167], v[176:179], v[56:59]
	v_mfma_f32_16x16x32_bf16 v[240:243], v[168:171], v[176:179], v[240:243]
	v_mfma_f32_16x16x32_bf16 v[120:123], v[172:175], v[176:179], v[120:123]
	ds_read_b128 v[176:179], v212 offset:10240
	s_add_u32 m0, s1, 45056
	s_nop 0
	global_load_lds_dwordx4 v159, s[86:87]
	s_add_u32 s86, s86, 128
	s_addc_u32 s87, s87, 0
	s_waitcnt lgkmcnt(6)
	v_mfma_f32_16x16x32_bf16 v[28:31], v[96:99], v[180:183], v[28:31]
	v_mfma_f32_16x16x32_bf16 v[60:63], v[164:167], v[180:183], v[60:63]
	v_mfma_f32_16x16x32_bf16 v[248:251], v[168:171], v[180:183], v[248:251]
	v_mfma_f32_16x16x32_bf16 v[124:127], v[172:175], v[180:183], v[124:127]
	s_waitcnt vmcnt(8)
	ds_read_b128 v[180:183], v212 offset:12288
	global_load_dwordx4 v[96:99], v142, s[84:85] offset:0
	s_waitcnt lgkmcnt(6)
	v_mfma_f32_16x16x32_bf16 v[0:3], v[64:67], v[188:191], v[0:3]
	v_mfma_f32_16x16x32_bf16 v[32:35], v[68:71], v[188:191], v[32:35]
	v_mfma_f32_16x16x32_bf16 v[144:147], v[72:75], v[188:191], v[144:147]
	v_mfma_f32_16x16x32_bf16 v[252:255], v[76:79], v[188:191], v[252:255]
	ds_read_b128 v[188:191], v212 offset:14336
	global_load_dwordx4 v[164:167], v150, s[84:85] offset:0
	s_waitcnt lgkmcnt(6)
	v_mfma_f32_16x16x32_bf16 v[4:7], v[64:67], v[192:195], v[4:7]
	v_mfma_f32_16x16x32_bf16 v[36:39], v[68:71], v[192:195], v[36:39]
	v_mfma_f32_16x16x32_bf16 v[184:187], v[72:75], v[192:195], v[184:187]
	v_mfma_f32_16x16x32_bf16 v[100:103], v[76:79], v[192:195], v[100:103]
	ds_read_b128 v[192:195], v213 offset:0
	global_load_dwordx4 v[168:171], v142, s[92:93] offset:0
	s_waitcnt lgkmcnt(6)
	v_mfma_f32_16x16x32_bf16 v[8:11], v[64:67], v[196:199], v[8:11]
	v_mfma_f32_16x16x32_bf16 v[40:43], v[68:71], v[196:199], v[40:43]
	v_mfma_f32_16x16x32_bf16 v[204:207], v[72:75], v[196:199], v[204:207]
	v_mfma_f32_16x16x32_bf16 v[104:107], v[76:79], v[196:199], v[104:107]
	ds_read_b128 v[196:199], v213 offset:2048
	global_load_dwordx4 v[172:175], v150, s[92:93] offset:0
	s_waitcnt lgkmcnt(6)
	v_mfma_f32_16x16x32_bf16 v[12:15], v[64:67], v[200:203], v[12:15]
	v_mfma_f32_16x16x32_bf16 v[44:47], v[68:71], v[200:203], v[44:47]
	v_mfma_f32_16x16x32_bf16 v[208:211], v[72:75], v[200:203], v[208:211]
	v_mfma_f32_16x16x32_bf16 v[108:111], v[76:79], v[200:203], v[108:111]
	ds_read_b128 v[200:203], v213 offset:4096
	s_waitcnt lgkmcnt(6)
	v_mfma_f32_16x16x32_bf16 v[16:19], v[64:67], v[160:163], v[16:19]
	v_mfma_f32_16x16x32_bf16 v[48:51], v[68:71], v[160:163], v[48:51]
	v_mfma_f32_16x16x32_bf16 v[232:235], v[72:75], v[160:163], v[232:235]
	v_mfma_f32_16x16x32_bf16 v[112:115], v[76:79], v[160:163], v[112:115]
	ds_read_b128 v[160:163], v213 offset:6144
	s_waitcnt lgkmcnt(6)
	v_mfma_f32_16x16x32_bf16 v[20:23], v[64:67], v[176:179], v[20:23]
	v_mfma_f32_16x16x32_bf16 v[52:55], v[68:71], v[176:179], v[52:55]
	v_mfma_f32_16x16x32_bf16 v[236:239], v[72:75], v[176:179], v[236:239]
	v_mfma_f32_16x16x32_bf16 v[116:119], v[76:79], v[176:179], v[116:119]
	ds_read_b128 v[176:179], v213 offset:8192
	s_waitcnt lgkmcnt(6)
	v_mfma_f32_16x16x32_bf16 v[24:27], v[64:67], v[180:183], v[24:27]
	v_mfma_f32_16x16x32_bf16 v[56:59], v[68:71], v[180:183], v[56:59]
	v_mfma_f32_16x16x32_bf16 v[240:243], v[72:75], v[180:183], v[240:243]
	v_mfma_f32_16x16x32_bf16 v[120:123], v[76:79], v[180:183], v[120:123]
	ds_read_b128 v[180:183], v213 offset:10240
	s_waitcnt lgkmcnt(6)
	v_mfma_f32_16x16x32_bf16 v[28:31], v[64:67], v[188:191], v[28:31]
	v_mfma_f32_16x16x32_bf16 v[60:63], v[68:71], v[188:191], v[60:63]
	v_mfma_f32_16x16x32_bf16 v[248:251], v[72:75], v[188:191], v[248:251]
	v_mfma_f32_16x16x32_bf16 v[124:127], v[76:79], v[188:191], v[124:127]
	s_waitcnt vmcnt(16)
	s_barrier
	s_waitcnt vmcnt(8)
	ds_read_b128 v[188:191], v213 offset:12288
	global_load_dwordx4 v[64:67], v142, s[84:85] offset:1024
	s_waitcnt lgkmcnt(6)
	v_mfma_f32_16x16x32_bf16 v[0:3], v[80:83], v[192:195], v[0:3]
	v_mfma_f32_16x16x32_bf16 v[32:35], v[84:87], v[192:195], v[32:35]
	v_mfma_f32_16x16x32_bf16 v[144:147], v[88:91], v[192:195], v[144:147]
	v_mfma_f32_16x16x32_bf16 v[252:255], v[92:95], v[192:195], v[252:255]
	ds_read_b128 v[192:195], v213 offset:14336
	global_load_dwordx4 v[68:71], v150, s[84:85] offset:1024
	s_waitcnt lgkmcnt(6)
	v_mfma_f32_16x16x32_bf16 v[4:7], v[80:83], v[196:199], v[4:7]
	v_mfma_f32_16x16x32_bf16 v[36:39], v[84:87], v[196:199], v[36:39]
	v_mfma_f32_16x16x32_bf16 v[184:187], v[88:91], v[196:199], v[184:187]
	v_mfma_f32_16x16x32_bf16 v[100:103], v[92:95], v[196:199], v[100:103]
	ds_read_b128 v[196:199], v212 offset:16384
	global_load_dwordx4 v[72:75], v142, s[92:93] offset:1024
	s_waitcnt lgkmcnt(6)
	v_mfma_f32_16x16x32_bf16 v[8:11], v[80:83], v[200:203], v[8:11]
	v_mfma_f32_16x16x32_bf16 v[40:43], v[84:87], v[200:203], v[40:43]
	v_mfma_f32_16x16x32_bf16 v[204:207], v[88:91], v[200:203], v[204:207]
	v_mfma_f32_16x16x32_bf16 v[104:107], v[92:95], v[200:203], v[104:107]
	ds_read_b128 v[200:203], v212 offset:18432
	global_load_dwordx4 v[76:79], v150, s[92:93] offset:1024
	s_add_u32 s84, s84, 0x800
	s_addc_u32 s85, s85, 0
	s_add_u32 s92, s92, 0x800
	s_addc_u32 s93, s93, 0
	s_waitcnt lgkmcnt(6)
	v_mfma_f32_16x16x32_bf16 v[12:15], v[80:83], v[160:163], v[12:15]
	v_mfma_f32_16x16x32_bf16 v[44:47], v[84:87], v[160:163], v[44:47]
	v_mfma_f32_16x16x32_bf16 v[208:211], v[88:91], v[160:163], v[208:211]
	v_mfma_f32_16x16x32_bf16 v[108:111], v[92:95], v[160:163], v[108:111]
	ds_read_b128 v[160:163], v212 offset:20480
	s_add_u32 m0, s1, 49152
	s_nop 0
	global_load_lds_dwordx4 v151, s[86:87]
	s_waitcnt lgkmcnt(6)
	v_mfma_f32_16x16x32_bf16 v[16:19], v[80:83], v[176:179], v[16:19]
	v_mfma_f32_16x16x32_bf16 v[48:51], v[84:87], v[176:179], v[48:51]
	v_mfma_f32_16x16x32_bf16 v[232:235], v[88:91], v[176:179], v[232:235]
	v_mfma_f32_16x16x32_bf16 v[112:115], v[92:95], v[176:179], v[112:115]
	ds_read_b128 v[176:179], v212 offset:22528
	s_add_u32 m0, s1, 53248
	s_nop 0
	global_load_lds_dwordx4 v156, s[86:87]
	s_waitcnt lgkmcnt(6)
	v_mfma_f32_16x16x32_bf16 v[20:23], v[80:83], v[180:183], v[20:23]
	v_mfma_f32_16x16x32_bf16 v[52:55], v[84:87], v[180:183], v[52:55]
	v_mfma_f32_16x16x32_bf16 v[236:239], v[88:91], v[180:183], v[236:239]
	v_mfma_f32_16x16x32_bf16 v[116:119], v[92:95], v[180:183], v[116:119]
	ds_read_b128 v[180:183], v212 offset:24576
	s_add_u32 m0, s1, 57344
	s_nop 0
	global_load_lds_dwordx4 v158, s[86:87]
	s_waitcnt lgkmcnt(6)
	v_mfma_f32_16x16x32_bf16 v[24:27], v[80:83], v[188:191], v[24:27]
	v_mfma_f32_16x16x32_bf16 v[56:59], v[84:87], v[188:191], v[56:59]
	v_mfma_f32_16x16x32_bf16 v[240:243], v[88:91], v[188:191], v[240:243]
	v_mfma_f32_16x16x32_bf16 v[120:123], v[92:95], v[188:191], v[120:123]
	ds_read_b128 v[188:191], v212 offset:26624
	s_add_u32 m0, s1, 61440
	s_nop 0
	global_load_lds_dwordx4 v159, s[86:87]
	s_add_u32 s86, s86, 128
	s_addc_u32 s87, s87, 0
	s_waitcnt lgkmcnt(6)
	v_mfma_f32_16x16x32_bf16 v[28:31], v[80:83], v[192:195], v[28:31]
	v_mfma_f32_16x16x32_bf16 v[60:63], v[84:87], v[192:195], v[60:63]
	v_mfma_f32_16x16x32_bf16 v[248:251], v[88:91], v[192:195], v[248:251]
	v_mfma_f32_16x16x32_bf16 v[124:127], v[92:95], v[192:195], v[124:127]
	s_waitcnt vmcnt(8)
	ds_read_b128 v[192:195], v212 offset:28672
	global_load_dwordx4 v[80:83], v142, s[84:85] offset:0
	s_waitcnt lgkmcnt(6)
	v_mfma_f32_16x16x32_bf16 v[0:3], v[96:99], v[196:199], v[0:3]
	v_mfma_f32_16x16x32_bf16 v[32:35], v[164:167], v[196:199], v[32:35]
	v_mfma_f32_16x16x32_bf16 v[144:147], v[168:171], v[196:199], v[144:147]
	v_mfma_f32_16x16x32_bf16 v[252:255], v[172:175], v[196:199], v[252:255]
	ds_read_b128 v[196:199], v212 offset:30720
	global_load_dwordx4 v[84:87], v150, s[84:85] offset:0
	s_waitcnt lgkmcnt(6)
	v_mfma_f32_16x16x32_bf16 v[4:7], v[96:99], v[200:203], v[4:7]
	v_mfma_f32_16x16x32_bf16 v[36:39], v[164:167], v[200:203], v[36:39]
	v_mfma_f32_16x16x32_bf16 v[184:187], v[168:171], v[200:203], v[184:187]
	v_mfma_f32_16x16x32_bf16 v[100:103], v[172:175], v[200:203], v[100:103]
	ds_read_b128 v[200:203], v213 offset:16384
	global_load_dwordx4 v[88:91], v142, s[92:93] offset:0
	s_waitcnt lgkmcnt(6)
	v_mfma_f32_16x16x32_bf16 v[8:11], v[96:99], v[160:163], v[8:11]
	v_mfma_f32_16x16x32_bf16 v[40:43], v[164:167], v[160:163], v[40:43]
	v_mfma_f32_16x16x32_bf16 v[204:207], v[168:171], v[160:163], v[204:207]
	v_mfma_f32_16x16x32_bf16 v[104:107], v[172:175], v[160:163], v[104:107]
	ds_read_b128 v[160:163], v213 offset:18432
	global_load_dwordx4 v[92:95], v150, s[92:93] offset:0
	s_waitcnt lgkmcnt(6)
	v_mfma_f32_16x16x32_bf16 v[12:15], v[96:99], v[176:179], v[12:15]
	v_mfma_f32_16x16x32_bf16 v[44:47], v[164:167], v[176:179], v[44:47]
	v_mfma_f32_16x16x32_bf16 v[208:211], v[168:171], v[176:179], v[208:211]
	v_mfma_f32_16x16x32_bf16 v[108:111], v[172:175], v[176:179], v[108:111]
	ds_read_b128 v[176:179], v213 offset:20480
	s_waitcnt lgkmcnt(6)
	v_mfma_f32_16x16x32_bf16 v[16:19], v[96:99], v[180:183], v[16:19]
	v_mfma_f32_16x16x32_bf16 v[48:51], v[164:167], v[180:183], v[48:51]
	v_mfma_f32_16x16x32_bf16 v[232:235], v[168:171], v[180:183], v[232:235]
	v_mfma_f32_16x16x32_bf16 v[112:115], v[172:175], v[180:183], v[112:115]
	ds_read_b128 v[180:183], v213 offset:22528
	s_waitcnt lgkmcnt(6)
	v_mfma_f32_16x16x32_bf16 v[20:23], v[96:99], v[188:191], v[20:23]
	v_mfma_f32_16x16x32_bf16 v[52:55], v[164:167], v[188:191], v[52:55]
	v_mfma_f32_16x16x32_bf16 v[236:239], v[168:171], v[188:191], v[236:239]
	v_mfma_f32_16x16x32_bf16 v[116:119], v[172:175], v[188:191], v[116:119]
	ds_read_b128 v[188:191], v213 offset:24576
	s_waitcnt lgkmcnt(6)
	v_mfma_f32_16x16x32_bf16 v[24:27], v[96:99], v[192:195], v[24:27]
	v_mfma_f32_16x16x32_bf16 v[56:59], v[164:167], v[192:195], v[56:59]
	v_mfma_f32_16x16x32_bf16 v[240:243], v[168:171], v[192:195], v[240:243]
	v_mfma_f32_16x16x32_bf16 v[120:123], v[172:175], v[192:195], v[120:123]
	ds_read_b128 v[192:195], v213 offset:26624
	s_waitcnt lgkmcnt(6)
	v_mfma_f32_16x16x32_bf16 v[28:31], v[96:99], v[196:199], v[28:31]
	v_mfma_f32_16x16x32_bf16 v[60:63], v[164:167], v[196:199], v[60:63]
	v_mfma_f32_16x16x32_bf16 v[248:251], v[168:171], v[196:199], v[248:251]
	v_mfma_f32_16x16x32_bf16 v[124:127], v[172:175], v[196:199], v[124:127]
	s_waitcnt vmcnt(16)
	s_barrier
	s_waitcnt vmcnt(8)
	ds_read_b128 v[196:199], v213 offset:28672
	global_load_dwordx4 v[96:99], v142, s[84:85] offset:1024
	s_waitcnt lgkmcnt(6)
	v_mfma_f32_16x16x32_bf16 v[0:3], v[64:67], v[200:203], v[0:3]
	v_mfma_f32_16x16x32_bf16 v[32:35], v[68:71], v[200:203], v[32:35]
	v_mfma_f32_16x16x32_bf16 v[144:147], v[72:75], v[200:203], v[144:147]
	v_mfma_f32_16x16x32_bf16 v[252:255], v[76:79], v[200:203], v[252:255]
	ds_read_b128 v[200:203], v213 offset:30720
	global_load_dwordx4 v[164:167], v150, s[84:85] offset:1024
	s_waitcnt lgkmcnt(6)
	v_mfma_f32_16x16x32_bf16 v[4:7], v[64:67], v[160:163], v[4:7]
	v_mfma_f32_16x16x32_bf16 v[36:39], v[68:71], v[160:163], v[36:39]
	v_mfma_f32_16x16x32_bf16 v[184:187], v[72:75], v[160:163], v[184:187]
	v_mfma_f32_16x16x32_bf16 v[100:103], v[76:79], v[160:163], v[100:103]
	ds_read_b128 v[160:163], v212 offset:32768
	global_load_dwordx4 v[168:171], v142, s[92:93] offset:1024
	s_waitcnt lgkmcnt(6)
	v_mfma_f32_16x16x32_bf16 v[8:11], v[64:67], v[176:179], v[8:11]
	v_mfma_f32_16x16x32_bf16 v[40:43], v[68:71], v[176:179], v[40:43]
	v_mfma_f32_16x16x32_bf16 v[204:207], v[72:75], v[176:179], v[204:207]
	v_mfma_f32_16x16x32_bf16 v[104:107], v[76:79], v[176:179], v[104:107]
	ds_read_b128 v[176:179], v212 offset:34816
	global_load_dwordx4 v[172:175], v150, s[92:93] offset:1024
	s_add_u32 s84, s84, 0x800
	s_addc_u32 s85, s85, 0
	s_add_u32 s92, s92, 0x800
	s_addc_u32 s93, s93, 0
	s_waitcnt lgkmcnt(6)
	v_mfma_f32_16x16x32_bf16 v[12:15], v[64:67], v[180:183], v[12:15]
	v_mfma_f32_16x16x32_bf16 v[44:47], v[68:71], v[180:183], v[44:47]
	v_mfma_f32_16x16x32_bf16 v[208:211], v[72:75], v[180:183], v[208:211]
	v_mfma_f32_16x16x32_bf16 v[108:111], v[76:79], v[180:183], v[108:111]
	ds_read_b128 v[180:183], v212 offset:36864
	s_waitcnt lgkmcnt(6)
	v_mfma_f32_16x16x32_bf16 v[16:19], v[64:67], v[188:191], v[16:19]
	v_mfma_f32_16x16x32_bf16 v[48:51], v[68:71], v[188:191], v[48:51]
	v_mfma_f32_16x16x32_bf16 v[232:235], v[72:75], v[188:191], v[232:235]
	v_mfma_f32_16x16x32_bf16 v[112:115], v[76:79], v[188:191], v[112:115]
	ds_read_b128 v[188:191], v212 offset:38912
	s_waitcnt lgkmcnt(6)
	v_mfma_f32_16x16x32_bf16 v[20:23], v[64:67], v[192:195], v[20:23]
	v_mfma_f32_16x16x32_bf16 v[52:55], v[68:71], v[192:195], v[52:55]
	v_mfma_f32_16x16x32_bf16 v[236:239], v[72:75], v[192:195], v[236:239]
	v_mfma_f32_16x16x32_bf16 v[116:119], v[76:79], v[192:195], v[116:119]
	ds_read_b128 v[192:195], v212 offset:40960
	s_waitcnt lgkmcnt(6)
	v_mfma_f32_16x16x32_bf16 v[24:27], v[64:67], v[196:199], v[24:27]
	v_mfma_f32_16x16x32_bf16 v[56:59], v[68:71], v[196:199], v[56:59]
	v_mfma_f32_16x16x32_bf16 v[240:243], v[72:75], v[196:199], v[240:243]
	v_mfma_f32_16x16x32_bf16 v[120:123], v[76:79], v[196:199], v[120:123]
	ds_read_b128 v[196:199], v212 offset:43008
	s_waitcnt lgkmcnt(6)
	v_mfma_f32_16x16x32_bf16 v[28:31], v[64:67], v[200:203], v[28:31]
	v_mfma_f32_16x16x32_bf16 v[60:63], v[68:71], v[200:203], v[60:63]
	v_mfma_f32_16x16x32_bf16 v[248:251], v[72:75], v[200:203], v[248:251]
	v_mfma_f32_16x16x32_bf16 v[124:127], v[76:79], v[200:203], v[124:127]
	s_waitcnt vmcnt(4)
	ds_read_b128 v[200:203], v212 offset:45056
	global_load_dwordx4 v[64:67], v142, s[84:85] offset:0
	s_waitcnt lgkmcnt(6)
	v_mfma_f32_16x16x32_bf16 v[0:3], v[80:83], v[160:163], v[0:3]
	v_mfma_f32_16x16x32_bf16 v[32:35], v[84:87], v[160:163], v[32:35]
	v_mfma_f32_16x16x32_bf16 v[144:147], v[88:91], v[160:163], v[144:147]
	v_mfma_f32_16x16x32_bf16 v[252:255], v[92:95], v[160:163], v[252:255]
	ds_read_b128 v[160:163], v212 offset:47104
	global_load_dwordx4 v[68:71], v150, s[84:85] offset:0
	s_waitcnt lgkmcnt(6)
	v_mfma_f32_16x16x32_bf16 v[4:7], v[80:83], v[176:179], v[4:7]
	v_mfma_f32_16x16x32_bf16 v[36:39], v[84:87], v[176:179], v[36:39]
	v_mfma_f32_16x16x32_bf16 v[184:187], v[88:91], v[176:179], v[184:187]
	v_mfma_f32_16x16x32_bf16 v[100:103], v[92:95], v[176:179], v[100:103]
	ds_read_b128 v[176:179], v213 offset:32768
	global_load_dwordx4 v[72:75], v142, s[92:93] offset:0
	s_waitcnt lgkmcnt(6)
	v_mfma_f32_16x16x32_bf16 v[8:11], v[80:83], v[180:183], v[8:11]
	v_mfma_f32_16x16x32_bf16 v[40:43], v[84:87], v[180:183], v[40:43]
	v_mfma_f32_16x16x32_bf16 v[204:207], v[88:91], v[180:183], v[204:207]
	v_mfma_f32_16x16x32_bf16 v[104:107], v[92:95], v[180:183], v[104:107]
	ds_read_b128 v[180:183], v213 offset:34816
	global_load_dwordx4 v[76:79], v150, s[92:93] offset:0
	s_waitcnt lgkmcnt(6)
	v_mfma_f32_16x16x32_bf16 v[12:15], v[80:83], v[188:191], v[12:15]
	v_mfma_f32_16x16x32_bf16 v[44:47], v[84:87], v[188:191], v[44:47]
	v_mfma_f32_16x16x32_bf16 v[208:211], v[88:91], v[188:191], v[208:211]
	v_mfma_f32_16x16x32_bf16 v[108:111], v[92:95], v[188:191], v[108:111]
	ds_read_b128 v[188:191], v213 offset:36864
	s_waitcnt lgkmcnt(6)
	v_mfma_f32_16x16x32_bf16 v[16:19], v[80:83], v[192:195], v[16:19]
	v_mfma_f32_16x16x32_bf16 v[48:51], v[84:87], v[192:195], v[48:51]
	v_mfma_f32_16x16x32_bf16 v[232:235], v[88:91], v[192:195], v[232:235]
	v_mfma_f32_16x16x32_bf16 v[112:115], v[92:95], v[192:195], v[112:115]
	ds_read_b128 v[192:195], v213 offset:38912
	s_waitcnt lgkmcnt(6)
	v_mfma_f32_16x16x32_bf16 v[20:23], v[80:83], v[196:199], v[20:23]
	v_mfma_f32_16x16x32_bf16 v[52:55], v[84:87], v[196:199], v[52:55]
	v_mfma_f32_16x16x32_bf16 v[236:239], v[88:91], v[196:199], v[236:239]
	v_mfma_f32_16x16x32_bf16 v[116:119], v[92:95], v[196:199], v[116:119]
	ds_read_b128 v[196:199], v213 offset:40960
	s_waitcnt lgkmcnt(6)
	v_mfma_f32_16x16x32_bf16 v[24:27], v[80:83], v[200:203], v[24:27]
	v_mfma_f32_16x16x32_bf16 v[56:59], v[84:87], v[200:203], v[56:59]
	v_mfma_f32_16x16x32_bf16 v[240:243], v[88:91], v[200:203], v[240:243]
	v_mfma_f32_16x16x32_bf16 v[120:123], v[92:95], v[200:203], v[120:123]
	ds_read_b128 v[200:203], v213 offset:43008
	s_waitcnt lgkmcnt(6)
	v_mfma_f32_16x16x32_bf16 v[28:31], v[80:83], v[160:163], v[28:31]
	v_mfma_f32_16x16x32_bf16 v[60:63], v[84:87], v[160:163], v[60:63]
	v_mfma_f32_16x16x32_bf16 v[248:251], v[88:91], v[160:163], v[248:251]
	v_mfma_f32_16x16x32_bf16 v[124:127], v[92:95], v[160:163], v[124:127]
	s_waitcnt vmcnt(12)
	s_barrier
	s_waitcnt vmcnt(4)
	ds_read_b128 v[160:163], v213 offset:45056
	global_load_dwordx4 v[80:83], v142, s[84:85] offset:1024
	s_waitcnt lgkmcnt(6)
	v_mfma_f32_16x16x32_bf16 v[0:3], v[96:99], v[176:179], v[0:3]
	v_mfma_f32_16x16x32_bf16 v[32:35], v[164:167], v[176:179], v[32:35]
	v_mfma_f32_16x16x32_bf16 v[144:147], v[168:171], v[176:179], v[144:147]
	v_mfma_f32_16x16x32_bf16 v[252:255], v[172:175], v[176:179], v[252:255]
	ds_read_b128 v[176:179], v213 offset:47104
	global_load_dwordx4 v[84:87], v150, s[84:85] offset:1024
	s_waitcnt lgkmcnt(6)
	v_mfma_f32_16x16x32_bf16 v[4:7], v[96:99], v[180:183], v[4:7]
	v_mfma_f32_16x16x32_bf16 v[36:39], v[164:167], v[180:183], v[36:39]
	v_mfma_f32_16x16x32_bf16 v[184:187], v[168:171], v[180:183], v[184:187]
	v_mfma_f32_16x16x32_bf16 v[100:103], v[172:175], v[180:183], v[100:103]
	ds_read_b128 v[180:183], v212 offset:49152
	global_load_dwordx4 v[88:91], v142, s[92:93] offset:1024
	s_waitcnt lgkmcnt(6)
	v_mfma_f32_16x16x32_bf16 v[8:11], v[96:99], v[188:191], v[8:11]
	v_mfma_f32_16x16x32_bf16 v[40:43], v[164:167], v[188:191], v[40:43]
	v_mfma_f32_16x16x32_bf16 v[204:207], v[168:171], v[188:191], v[204:207]
	v_mfma_f32_16x16x32_bf16 v[104:107], v[172:175], v[188:191], v[104:107]
	ds_read_b128 v[188:191], v212 offset:51200
	global_load_dwordx4 v[92:95], v150, s[92:93] offset:1024
	s_add_u32 s84, s84, 0x800
	s_addc_u32 s85, s85, 0
	s_add_u32 s92, s92, 0x800
	s_addc_u32 s93, s93, 0
	s_waitcnt lgkmcnt(6)
	v_mfma_f32_16x16x32_bf16 v[12:15], v[96:99], v[192:195], v[12:15]
	v_mfma_f32_16x16x32_bf16 v[44:47], v[164:167], v[192:195], v[44:47]
	v_mfma_f32_16x16x32_bf16 v[208:211], v[168:171], v[192:195], v[208:211]
	v_mfma_f32_16x16x32_bf16 v[108:111], v[172:175], v[192:195], v[108:111]
	ds_read_b128 v[192:195], v212 offset:53248
	s_waitcnt lgkmcnt(6)
	v_mfma_f32_16x16x32_bf16 v[16:19], v[96:99], v[196:199], v[16:19]
	v_mfma_f32_16x16x32_bf16 v[48:51], v[164:167], v[196:199], v[48:51]
	v_mfma_f32_16x16x32_bf16 v[232:235], v[168:171], v[196:199], v[232:235]
	v_mfma_f32_16x16x32_bf16 v[112:115], v[172:175], v[196:199], v[112:115]
	ds_read_b128 v[196:199], v212 offset:55296
	s_waitcnt lgkmcnt(6)
	v_mfma_f32_16x16x32_bf16 v[20:23], v[96:99], v[200:203], v[20:23]
	v_mfma_f32_16x16x32_bf16 v[52:55], v[164:167], v[200:203], v[52:55]
	v_mfma_f32_16x16x32_bf16 v[236:239], v[168:171], v[200:203], v[236:239]
	v_mfma_f32_16x16x32_bf16 v[116:119], v[172:175], v[200:203], v[116:119]
	ds_read_b128 v[200:203], v212 offset:57344
	s_waitcnt lgkmcnt(6)
	v_mfma_f32_16x16x32_bf16 v[24:27], v[96:99], v[160:163], v[24:27]
	v_mfma_f32_16x16x32_bf16 v[56:59], v[164:167], v[160:163], v[56:59]
	v_mfma_f32_16x16x32_bf16 v[240:243], v[168:171], v[160:163], v[240:243]
	v_mfma_f32_16x16x32_bf16 v[120:123], v[172:175], v[160:163], v[120:123]
	ds_read_b128 v[160:163], v212 offset:59392
	s_waitcnt lgkmcnt(6)
	v_mfma_f32_16x16x32_bf16 v[28:31], v[96:99], v[176:179], v[28:31]
	v_mfma_f32_16x16x32_bf16 v[60:63], v[164:167], v[176:179], v[60:63]
	v_mfma_f32_16x16x32_bf16 v[248:251], v[168:171], v[176:179], v[248:251]
	v_mfma_f32_16x16x32_bf16 v[124:127], v[172:175], v[176:179], v[124:127]
	s_waitcnt vmcnt(4)
	ds_read_b128 v[176:179], v212 offset:61440
	s_waitcnt lgkmcnt(6)
	v_mfma_f32_16x16x32_bf16 v[0:3], v[64:67], v[180:183], v[0:3]
	v_mfma_f32_16x16x32_bf16 v[32:35], v[68:71], v[180:183], v[32:35]
	v_mfma_f32_16x16x32_bf16 v[144:147], v[72:75], v[180:183], v[144:147]
	v_mfma_f32_16x16x32_bf16 v[252:255], v[76:79], v[180:183], v[252:255]
	ds_read_b128 v[180:183], v212 offset:63488
	s_waitcnt lgkmcnt(6)
	v_mfma_f32_16x16x32_bf16 v[4:7], v[64:67], v[188:191], v[4:7]
	v_mfma_f32_16x16x32_bf16 v[36:39], v[68:71], v[188:191], v[36:39]
	v_mfma_f32_16x16x32_bf16 v[184:187], v[72:75], v[188:191], v[184:187]
	v_mfma_f32_16x16x32_bf16 v[100:103], v[76:79], v[188:191], v[100:103]
	ds_read_b128 v[188:191], v213 offset:49152
	s_waitcnt lgkmcnt(6)
	v_mfma_f32_16x16x32_bf16 v[8:11], v[64:67], v[192:195], v[8:11]
	v_mfma_f32_16x16x32_bf16 v[40:43], v[68:71], v[192:195], v[40:43]
	v_mfma_f32_16x16x32_bf16 v[204:207], v[72:75], v[192:195], v[204:207]
	v_mfma_f32_16x16x32_bf16 v[104:107], v[76:79], v[192:195], v[104:107]
	ds_read_b128 v[192:195], v213 offset:51200
	s_waitcnt lgkmcnt(6)
	v_mfma_f32_16x16x32_bf16 v[12:15], v[64:67], v[196:199], v[12:15]
	v_mfma_f32_16x16x32_bf16 v[44:47], v[68:71], v[196:199], v[44:47]
	v_mfma_f32_16x16x32_bf16 v[208:211], v[72:75], v[196:199], v[208:211]
	v_mfma_f32_16x16x32_bf16 v[108:111], v[76:79], v[196:199], v[108:111]
	ds_read_b128 v[196:199], v213 offset:53248
	s_waitcnt lgkmcnt(6)
	v_mfma_f32_16x16x32_bf16 v[16:19], v[64:67], v[200:203], v[16:19]
	v_mfma_f32_16x16x32_bf16 v[48:51], v[68:71], v[200:203], v[48:51]
	v_mfma_f32_16x16x32_bf16 v[232:235], v[72:75], v[200:203], v[232:235]
	v_mfma_f32_16x16x32_bf16 v[112:115], v[76:79], v[200:203], v[112:115]
	ds_read_b128 v[200:203], v213 offset:55296
	s_waitcnt lgkmcnt(6)
	v_mfma_f32_16x16x32_bf16 v[20:23], v[64:67], v[160:163], v[20:23]
	v_mfma_f32_16x16x32_bf16 v[52:55], v[68:71], v[160:163], v[52:55]
	v_mfma_f32_16x16x32_bf16 v[236:239], v[72:75], v[160:163], v[236:239]
	v_mfma_f32_16x16x32_bf16 v[116:119], v[76:79], v[160:163], v[116:119]
	ds_read_b128 v[160:163], v213 offset:57344
	s_waitcnt lgkmcnt(6)
	v_mfma_f32_16x16x32_bf16 v[24:27], v[64:67], v[176:179], v[24:27]
	v_mfma_f32_16x16x32_bf16 v[56:59], v[68:71], v[176:179], v[56:59]
	v_mfma_f32_16x16x32_bf16 v[240:243], v[72:75], v[176:179], v[240:243]
	v_mfma_f32_16x16x32_bf16 v[120:123], v[76:79], v[176:179], v[120:123]
	ds_read_b128 v[176:179], v213 offset:59392
	s_waitcnt lgkmcnt(6)
	v_mfma_f32_16x16x32_bf16 v[28:31], v[64:67], v[180:183], v[28:31]
	v_mfma_f32_16x16x32_bf16 v[60:63], v[68:71], v[180:183], v[60:63]
	v_mfma_f32_16x16x32_bf16 v[248:251], v[72:75], v[180:183], v[248:251]
	v_mfma_f32_16x16x32_bf16 v[124:127], v[76:79], v[180:183], v[124:127]
	s_waitcnt vmcnt(0)
	ds_read_b128 v[180:183], v213 offset:61440
	s_waitcnt lgkmcnt(6)
	v_mfma_f32_16x16x32_bf16 v[0:3], v[80:83], v[188:191], v[0:3]
	v_mfma_f32_16x16x32_bf16 v[32:35], v[84:87], v[188:191], v[32:35]
	v_mfma_f32_16x16x32_bf16 v[144:147], v[88:91], v[188:191], v[144:147]
	v_mfma_f32_16x16x32_bf16 v[252:255], v[92:95], v[188:191], v[252:255]
	ds_read_b128 v[188:191], v213 offset:63488
	s_waitcnt lgkmcnt(6)
	v_mfma_f32_16x16x32_bf16 v[4:7], v[80:83], v[192:195], v[4:7]
	v_mfma_f32_16x16x32_bf16 v[36:39], v[84:87], v[192:195], v[36:39]
	v_mfma_f32_16x16x32_bf16 v[184:187], v[88:91], v[192:195], v[184:187]
	v_mfma_f32_16x16x32_bf16 v[100:103], v[92:95], v[192:195], v[100:103]
	s_waitcnt lgkmcnt(5)
	v_mfma_f32_16x16x32_bf16 v[8:11], v[80:83], v[196:199], v[8:11]
	v_mfma_f32_16x16x32_bf16 v[40:43], v[84:87], v[196:199], v[40:43]
	v_mfma_f32_16x16x32_bf16 v[204:207], v[88:91], v[196:199], v[204:207]
	v_mfma_f32_16x16x32_bf16 v[104:107], v[92:95], v[196:199], v[104:107]
	s_waitcnt lgkmcnt(4)
	v_mfma_f32_16x16x32_bf16 v[12:15], v[80:83], v[200:203], v[12:15]
	v_mfma_f32_16x16x32_bf16 v[44:47], v[84:87], v[200:203], v[44:47]
	v_mfma_f32_16x16x32_bf16 v[208:211], v[88:91], v[200:203], v[208:211]
	v_mfma_f32_16x16x32_bf16 v[108:111], v[92:95], v[200:203], v[108:111]
	s_waitcnt lgkmcnt(3)
	v_mfma_f32_16x16x32_bf16 v[16:19], v[80:83], v[160:163], v[16:19]
	v_mfma_f32_16x16x32_bf16 v[48:51], v[84:87], v[160:163], v[48:51]
	v_mfma_f32_16x16x32_bf16 v[232:235], v[88:91], v[160:163], v[232:235]
	v_mfma_f32_16x16x32_bf16 v[112:115], v[92:95], v[160:163], v[112:115]
	s_waitcnt lgkmcnt(2)
	v_mfma_f32_16x16x32_bf16 v[20:23], v[80:83], v[176:179], v[20:23]
	v_mfma_f32_16x16x32_bf16 v[52:55], v[84:87], v[176:179], v[52:55]
	v_mfma_f32_16x16x32_bf16 v[236:239], v[88:91], v[176:179], v[236:239]
	v_mfma_f32_16x16x32_bf16 v[116:119], v[92:95], v[176:179], v[116:119]
	s_waitcnt lgkmcnt(1)
	v_mfma_f32_16x16x32_bf16 v[24:27], v[80:83], v[180:183], v[24:27]
	v_mfma_f32_16x16x32_bf16 v[56:59], v[84:87], v[180:183], v[56:59]
	v_mfma_f32_16x16x32_bf16 v[240:243], v[88:91], v[180:183], v[240:243]
	v_mfma_f32_16x16x32_bf16 v[120:123], v[92:95], v[180:183], v[120:123]
	s_waitcnt lgkmcnt(0)
	v_mfma_f32_16x16x32_bf16 v[28:31], v[80:83], v[188:191], v[28:31]
	v_mfma_f32_16x16x32_bf16 v[60:63], v[84:87], v[188:191], v[60:63]
	v_mfma_f32_16x16x32_bf16 v[248:251], v[88:91], v[188:191], v[248:251]
	v_mfma_f32_16x16x32_bf16 v[124:127], v[92:95], v[188:191], v[124:127]
	s_nop 7
	s_nop 7
	s_waitcnt vmcnt(0) lgkmcnt(0)
	s_setprio 0
	s_barrier
	v_mov_b32_e32 v150, v100
	v_mov_b32_e32 v151, v101
	v_mov_b32_e32 v156, v102
	v_mov_b32_e32 v158, v103
	v_mov_b32_e32 v159, v104
	v_mov_b32_e32 v160, v105
	v_mov_b32_e32 v183, v106
	v_mov_b32_e32 v188, v107
	v_mov_b32_e32 v189, v108
	v_mov_b32_e32 v212, v109
	v_mov_b32_e32 v213, v110
	v_mov_b32_e32 v214, v111
	v_mov_b32_e32 v216, v112
	v_mov_b32_e32 v218, v113
	v_mov_b32_e32 v220, v114
	v_mov_b32_e32 v222, v115
	v_mov_b32_e32 v224, v116
	v_mov_b32_e32 v226, v117
	v_mov_b32_e32 v228, v118
	v_mov_b32_e32 v230, v119
	v_mov_b32_e32 v231, v120
	v_mov_b32_e32 v244, v121
	v_mov_b32_e32 v245, v122
	ds_write_b32 v140, v123 offset:40960
	ds_write_b32 v140, v124 offset:41984
	ds_write_b32 v140, v125 offset:43008
	ds_write_b32 v140, v126 offset:44032
	ds_write_b32 v140, v127 offset:45056
	v_lshlrev_b32_e32 v64, 13, v135
	v_lshl_add_u32 v65, v134, 3, v138
	v_lshl_or_b32 v66, v134, 11, v64
	v_lshlrev_b32_e32 v68, 5, v138
	v_or3_b32 v161, v64, v137, v68
	v_lshl_or_b32 v162, v65, 2, v66
	v_add_u32_e32 v68, 0x60, v65
	v_add_u32_e32 v65, 0x70, v65
	v_and_b32_e32 v68, 0x7f, v68
	v_and_b32_e32 v65, 0x7f, v65
	v_lshl_or_b32 v163, v68, 2, v66
	v_lshl_or_b32 v164, v65, 2, v66
	v_add_u32_e32 v66, 8, v133
	v_and_b32_e32 v66, 0x78, v66
	v_lshlrev_b32_e32 v65, 9, v136
	v_lshlrev_b32_e32 v66, 2, v66
	v_or3_b32 v166, v64, v65, v66
	v_add_u32_e32 v66, 16, v133
	v_and_b32_e32 v66, 0x78, v66
	v_lshlrev_b32_e32 v65, 9, v132
	v_lshlrev_b32_e32 v66, 2, v66
	v_or3_b32 v168, v64, v65, v66
	v_add_u32_e32 v66, 24, v133
	v_and_b32_e32 v66, 0x78, v66
	v_lshlrev_b32_e32 v67, 5, v135
	v_lshlrev_b32_e32 v65, 9, v130
	v_lshlrev_b32_e32 v66, 2, v66
	v_or3_b32 v170, v64, v65, v66
	v_or_b32_e32 v64, 16, v67
	v_add_u32_e32 v68, 0x100, v131
	v_add_u32_e32 v69, 0x200, v131
	v_add_u32_e32 v70, 0x300, v131
	v_add_u32_e32 v71, 0x500, v131
	v_add_u32_e32 v72, 0x600, v131
	v_add_u32_e32 v73, 0x700, v131
	v_or_b32_e32 v172, v64, v134
	v_or_b32_e32 v173, v136, v64
	v_or_b32_e32 v174, v132, v64
	v_or_b32_e32 v175, v130, v64
	v_and_b32_e32 v64, 24, v153
	s_movk_i32 s90, 0x3c0
	v_lshrrev_b32_e32 v176, 4, v68
	v_lshrrev_b32_e32 v177, 4, v69
	v_lshrrev_b32_e32 v178, 4, v70
	v_lshrrev_b32_e32 v180, 4, v71
	v_lshrrev_b32_e32 v181, 4, v72
	v_lshrrev_b32_e32 v182, 4, v73
	v_or_b32_e32 v165, v134, v67
	v_or_b32_e32 v167, v136, v67
	v_or_b32_e32 v169, v132, v67
	v_or_b32_e32 v171, v130, v67
	v_and_or_b32 v64, v131, s90, v64
	v_mul_u32_u24_e32 v65, 0x110, v138
	v_lshlrev_b32_e32 v66, 4, v138
	v_mul_u32_u24_e32 v67, 0x110, v128
	v_mul_u32_u24_e32 v68, 0x110, v176
	v_mul_u32_u24_e32 v69, 0x110, v177
	v_mul_u32_u24_e32 v70, 0x110, v178
	v_mul_u32_u24_e32 v71, 0x110, v180
	v_mul_u32_u24_e32 v72, 0x110, v181
	v_mul_u32_u24_e32 v73, 0x110, v182
	v_or_b32_e32 v179, 64, v128
	v_lshlrev_b32_e32 v190, 2, v138
	v_add_u32_e32 v191, v64, v65
	v_add_u32_e32 v192, v66, v67
	v_add_u32_e32 v193, v66, v68
	v_add_u32_e32 v194, v66, v69
	v_add_u32_e32 v195, v66, v70
	v_add_u32_e32 v196, v66, v71
	v_add_u32_e32 v197, v66, v72
	v_add_u32_e32 v198, v66, v73
	v_mbcnt_hi_u32_b32 v199, -1, v155
	s_waitcnt lgkmcnt(0)
	s_mov_b64 s[6:7], -1
	s_cmp_lt_i32 s77, 5
	s_branch .Lmy_ip0_epi
